# sshead: P8/P12 ss[row] loads issued at tile head before K-loop instead of at epilogue start
# baseline (speedup 1.0000x reference)
.LBB0_1038:
	s_ashr_i32 s23, s22, 31
	v_cmp_lt_i64_e32 vcc, s[0:1], v[140:141]
	s_lshl_b64 s[0:1], s[22:23], 20
	s_add_u32 s24, s6, s0
	s_addc_u32 s25, s7, s1
	s_and_b64 s[0:1], vcc, exec
	s_cselect_b32 s23, s25, s35
	s_cselect_b32 s56, s24, s34
	s_ashr_i32 s21, s20, 31
	s_lshl_b64 s[0:1], s[20:21], 20
	s_add_u32 s26, s36, s0
	s_addc_u32 s27, s37, s1
	s_and_b64 s[0:1], vcc, exec
	s_cselect_b32 s21, s27, s31
	s_cselect_b32 s57, s26, s30
	s_add_u32 s0, s34, 0x80080
	s_addc_u32 s1, s35, 0
	s_add_u32 s58, s30, 0x100
	v_mov_b32_e32 v0, 0
	s_addc_u32 s59, s31, 0
	s_mov_b32 s60, -2
	v_mov_b32_e32 v1, v0
	v_mov_b32_e32 v2, v0
	v_mov_b32_e32 v3, v0
	v_mov_b32_e32 v4, v0
	v_mov_b32_e32 v5, v0
	v_mov_b32_e32 v6, v0
	v_mov_b32_e32 v7, v0
	v_mov_b32_e32 v16, v0
	v_mov_b32_e32 v17, v0
	v_mov_b32_e32 v18, v0
	v_mov_b32_e32 v19, v0
	v_mov_b32_e32 v20, v0
	v_mov_b32_e32 v21, v0
	v_mov_b32_e32 v22, v0
	v_mov_b32_e32 v23, v0
	v_mov_b32_e32 v32, v0
	v_mov_b32_e32 v33, v0
	v_mov_b32_e32 v34, v0
	v_mov_b32_e32 v35, v0
	v_mov_b32_e32 v36, v0
	v_mov_b32_e32 v37, v0
	v_mov_b32_e32 v38, v0
	v_mov_b32_e32 v39, v0
	v_mov_b32_e32 v48, v0
	v_mov_b32_e32 v49, v0
	v_mov_b32_e32 v50, v0
	v_mov_b32_e32 v51, v0
	v_mov_b32_e32 v52, v0
	v_mov_b32_e32 v53, v0
	v_mov_b32_e32 v54, v0
	v_mov_b32_e32 v55, v0
	v_mov_b32_e32 v8, v0
	v_mov_b32_e32 v9, v0
	v_mov_b32_e32 v10, v0
	v_mov_b32_e32 v11, v0
	v_mov_b32_e32 v12, v0
	v_mov_b32_e32 v13, v0
	v_mov_b32_e32 v14, v0
	v_mov_b32_e32 v15, v0
	v_mov_b32_e32 v24, v0
	v_mov_b32_e32 v25, v0
	v_mov_b32_e32 v26, v0
	v_mov_b32_e32 v27, v0
	v_mov_b32_e32 v28, v0
	v_mov_b32_e32 v29, v0
	v_mov_b32_e32 v30, v0
	v_mov_b32_e32 v31, v0
	v_mov_b32_e32 v40, v0
	v_mov_b32_e32 v41, v0
	v_mov_b32_e32 v42, v0
	v_mov_b32_e32 v43, v0
	v_mov_b32_e32 v44, v0
	v_mov_b32_e32 v45, v0
	v_mov_b32_e32 v46, v0
	v_mov_b32_e32 v47, v0
	v_mov_b32_e32 v56, v0
	v_mov_b32_e32 v57, v0
	v_mov_b32_e32 v58, v0
	v_mov_b32_e32 v59, v0
	v_mov_b32_e32 v60, v0
	v_mov_b32_e32 v61, v0
	v_mov_b32_e32 v62, v0
	v_mov_b32_e32 v63, v0
	v_mov_b32_e32 v64, v0
	v_mov_b32_e32 v65, v0
	v_mov_b32_e32 v66, v0
	v_mov_b32_e32 v67, v0
	v_mov_b32_e32 v68, v0
	v_mov_b32_e32 v69, v0
	v_mov_b32_e32 v70, v0
	v_mov_b32_e32 v71, v0
	v_mov_b32_e32 v80, v0
	v_mov_b32_e32 v81, v0
	v_mov_b32_e32 v82, v0
	v_mov_b32_e32 v83, v0
	v_mov_b32_e32 v84, v0
	v_mov_b32_e32 v85, v0
	v_mov_b32_e32 v86, v0
	v_mov_b32_e32 v87, v0
	v_mov_b32_e32 v96, v0
	v_mov_b32_e32 v97, v0
	v_mov_b32_e32 v98, v0
	v_mov_b32_e32 v99, v0
	v_mov_b32_e32 v100, v0
	v_mov_b32_e32 v101, v0
	v_mov_b32_e32 v102, v0
	v_mov_b32_e32 v103, v0
	v_mov_b32_e32 v112, v0
	v_mov_b32_e32 v113, v0
	v_mov_b32_e32 v114, v0
	v_mov_b32_e32 v115, v0
	v_mov_b32_e32 v116, v0
	v_mov_b32_e32 v117, v0
	v_mov_b32_e32 v118, v0
	v_mov_b32_e32 v119, v0
	v_mov_b32_e32 v72, v0
	v_mov_b32_e32 v73, v0
	v_mov_b32_e32 v74, v0
	v_mov_b32_e32 v75, v0
	v_mov_b32_e32 v76, v0
	v_mov_b32_e32 v77, v0
	v_mov_b32_e32 v78, v0
	v_mov_b32_e32 v79, v0
	v_mov_b32_e32 v88, v0
	v_mov_b32_e32 v89, v0
	v_mov_b32_e32 v90, v0
	v_mov_b32_e32 v91, v0
	v_mov_b32_e32 v92, v0
	v_mov_b32_e32 v93, v0
	v_mov_b32_e32 v94, v0
	v_mov_b32_e32 v95, v0
	v_mov_b32_e32 v104, v0
	v_mov_b32_e32 v105, v0
	v_mov_b32_e32 v106, v0
	v_mov_b32_e32 v107, v0
	v_mov_b32_e32 v108, v0
	v_mov_b32_e32 v109, v0
	v_mov_b32_e32 v110, v0
	v_mov_b32_e32 v111, v0
	v_mov_b32_e32 v120, v0
	v_mov_b32_e32 v121, v0
	v_mov_b32_e32 v122, v0
	v_mov_b32_e32 v123, v0
	v_mov_b32_e32 v124, v0
	v_mov_b32_e32 v125, v0
	v_mov_b32_e32 v126, v0
	v_mov_b32_e32 v127, v0
	v_lshl_add_u32 v252, s28, 8, v148
	v_ashrrev_i32_e32 v253, 31, v252
	v_lshl_add_u64 v[254:255], v[252:253], 2, s[8:9]
	global_load_dword v236, v[254:255], off
	global_load_dword v237, v[254:255], off offset:64
	global_load_dword v238, v[254:255], off offset:128
	global_load_dword v239, v[254:255], off offset:192
	global_load_dword v240, v[254:255], off offset:512
	global_load_dword v241, v[254:255], off offset:576
	global_load_dword v242, v[254:255], off offset:640
	global_load_dword v243, v[254:255], off offset:704
.LBB0_1039:
	ds_read_b128 v[144:147], v151
	ds_read_b128 v[156:159], v151 offset:1024
	ds_read_b128 v[160:163], v151 offset:2048
	ds_read_b128 v[164:167], v151 offset:3072
	s_add_u32 s30, s0, 0xfff80080
	s_addc_u32 s31, s1, -1
	s_cmp_eq_u32 s60, 28
	s_cselect_b32 s35, s23, s31
	s_cselect_b32 s34, s56, s30
	s_cselect_b32 s31, s21, s59
	s_cselect_b32 s30, s57, s58
	v_lshl_add_u64 v[168:169], s[0:1], 0, v[136:137]
	s_add_i32 m0, s29, 0xc000
	ds_read_b128 v[172:175], v152
	ds_read_b128 v[176:179], v152 offset:1024
	ds_read_b128 v[180:183], v152 offset:2048
	ds_read_b128 v[184:187], v152 offset:3072
	ds_read_b128 v[188:191], v152 offset:4096
	ds_read_b128 v[192:195], v152 offset:5120
	ds_read_b128 v[196:199], v152 offset:6144
	ds_read_b128 v[200:203], v152 offset:7168
	global_load_lds_dwordx4 v[168:169], off
	v_lshl_add_u64 v[168:169], s[0:1], 0, v[138:139]
	s_add_i32 m0, s29, 0xe000
	s_nop 0
	global_load_lds_dwordx4 v[168:169], off
	s_waitcnt lgkmcnt(8)
	s_barrier
	s_waitcnt lgkmcnt(0)
	s_setprio 1
	s_waitcnt lgkmcnt(0)
	v_mfma_f32_16x16x32_bf16 v[124:127], v[144:147], v[172:175], v[124:127]
	v_mfma_f32_16x16x32_bf16 v[120:123], v[160:163], v[172:175], v[120:123]
	v_mfma_f32_16x16x32_bf16 v[108:111], v[144:147], v[180:183], v[108:111]
	v_mfma_f32_16x16x32_bf16 v[104:107], v[160:163], v[180:183], v[104:107]
	v_mfma_f32_16x16x32_bf16 v[92:95], v[144:147], v[188:191], v[92:95]
	v_mfma_f32_16x16x32_bf16 v[88:91], v[160:163], v[188:191], v[88:91]
	v_mfma_f32_16x16x32_bf16 v[76:79], v[144:147], v[196:199], v[76:79]
	v_mfma_f32_16x16x32_bf16 v[72:75], v[160:163], v[196:199], v[72:75]
	v_mfma_f32_16x16x32_bf16 v[124:127], v[156:159], v[176:179], v[124:127]
	v_mfma_f32_16x16x32_bf16 v[120:123], v[164:167], v[176:179], v[120:123]
	v_mfma_f32_16x16x32_bf16 v[108:111], v[156:159], v[184:187], v[108:111]
	v_mfma_f32_16x16x32_bf16 v[104:107], v[164:167], v[184:187], v[104:107]
	v_mfma_f32_16x16x32_bf16 v[92:95], v[156:159], v[192:195], v[92:95]
	v_mfma_f32_16x16x32_bf16 v[88:91], v[164:167], v[192:195], v[88:91]
	v_mfma_f32_16x16x32_bf16 v[76:79], v[156:159], v[200:203], v[76:79]
	v_mfma_f32_16x16x32_bf16 v[72:75], v[164:167], v[200:203], v[72:75]
	s_setprio 0
	s_barrier
	s_add_i32 s61, s48, s38
	v_lshl_add_u64 v[168:169], s[30:31], 0, v[130:131]
	s_mov_b32 m0, s61
	ds_read_b128 v[204:207], v153
	ds_read_b128 v[208:211], v153 offset:1024
	ds_read_b128 v[212:215], v153 offset:2048
	ds_read_b128 v[216:219], v153 offset:3072
	global_load_lds_dwordx4 v[168:169], off
	v_lshl_add_u64 v[220:221], s[30:31], 0, v[134:135]
	s_add_i32 m0, s61, 0x2000
	s_nop 0
	global_load_lds_dwordx4 v[220:221], off
	s_barrier
	s_waitcnt lgkmcnt(0)
	s_setprio 1
	s_waitcnt lgkmcnt(0)
	v_mfma_f32_16x16x32_bf16 v[116:119], v[204:207], v[172:175], v[116:119]
	v_mfma_f32_16x16x32_bf16 v[112:115], v[212:215], v[172:175], v[112:115]
	v_mfma_f32_16x16x32_bf16 v[100:103], v[204:207], v[180:183], v[100:103]
	v_mfma_f32_16x16x32_bf16 v[96:99], v[212:215], v[180:183], v[96:99]
	v_mfma_f32_16x16x32_bf16 v[84:87], v[204:207], v[188:191], v[84:87]
	v_mfma_f32_16x16x32_bf16 v[80:83], v[212:215], v[188:191], v[80:83]
	v_mfma_f32_16x16x32_bf16 v[68:71], v[204:207], v[196:199], v[68:71]
	v_mfma_f32_16x16x32_bf16 v[64:67], v[212:215], v[196:199], v[64:67]
	v_mfma_f32_16x16x32_bf16 v[116:119], v[208:211], v[176:179], v[116:119]
	v_mfma_f32_16x16x32_bf16 v[112:115], v[216:219], v[176:179], v[112:115]
	v_mfma_f32_16x16x32_bf16 v[100:103], v[208:211], v[184:187], v[100:103]
	v_mfma_f32_16x16x32_bf16 v[96:99], v[216:219], v[184:187], v[96:99]
	v_mfma_f32_16x16x32_bf16 v[84:87], v[208:211], v[192:195], v[84:87]
	v_mfma_f32_16x16x32_bf16 v[80:83], v[216:219], v[192:195], v[80:83]
	v_mfma_f32_16x16x32_bf16 v[68:71], v[208:211], v[200:203], v[68:71]
	v_mfma_f32_16x16x32_bf16 v[64:67], v[216:219], v[200:203], v[64:67]
	s_setprio 0
	s_mov_b32 m0, s29
	v_lshl_add_u64 v[222:223], s[34:35], 0, v[128:129]
	s_barrier
	ds_read_b128 v[172:175], v152 offset:16384
	ds_read_b128 v[176:179], v152 offset:17408
	ds_read_b128 v[180:183], v152 offset:18432
	ds_read_b128 v[184:187], v152 offset:19456
	ds_read_b128 v[188:191], v152 offset:20480
	ds_read_b128 v[192:195], v152 offset:21504
	ds_read_b128 v[196:199], v152 offset:22528
	ds_read_b128 v[200:203], v152 offset:23552
	global_load_lds_dwordx4 v[222:223], off
	v_lshl_add_u64 v[224:225], s[34:35], 0, v[132:133]
	s_mov_b32 m0, s40
	s_nop 0
	global_load_lds_dwordx4 v[224:225], off
	s_barrier
	s_waitcnt lgkmcnt(0)
	s_setprio 1
	s_waitcnt lgkmcnt(0)
	v_mfma_f32_16x16x32_bf16 v[60:63], v[144:147], v[172:175], v[60:63]
	v_mfma_f32_16x16x32_bf16 v[56:59], v[160:163], v[172:175], v[56:59]
	v_mfma_f32_16x16x32_bf16 v[44:47], v[144:147], v[180:183], v[44:47]
	v_mfma_f32_16x16x32_bf16 v[40:43], v[160:163], v[180:183], v[40:43]
	v_mfma_f32_16x16x32_bf16 v[28:31], v[144:147], v[188:191], v[28:31]
	v_mfma_f32_16x16x32_bf16 v[24:27], v[160:163], v[188:191], v[24:27]
	v_mfma_f32_16x16x32_bf16 v[12:15], v[144:147], v[196:199], v[12:15]
	v_mfma_f32_16x16x32_bf16 v[8:11], v[160:163], v[196:199], v[8:11]
	v_mfma_f32_16x16x32_bf16 v[60:63], v[156:159], v[176:179], v[60:63]
	v_mfma_f32_16x16x32_bf16 v[56:59], v[164:167], v[176:179], v[56:59]
	v_mfma_f32_16x16x32_bf16 v[44:47], v[156:159], v[184:187], v[44:47]
	v_mfma_f32_16x16x32_bf16 v[40:43], v[164:167], v[184:187], v[40:43]
	v_mfma_f32_16x16x32_bf16 v[28:31], v[156:159], v[192:195], v[28:31]
	v_mfma_f32_16x16x32_bf16 v[24:27], v[164:167], v[192:195], v[24:27]
	v_mfma_f32_16x16x32_bf16 v[12:15], v[156:159], v[200:203], v[12:15]
	v_mfma_f32_16x16x32_bf16 v[8:11], v[164:167], v[200:203], v[8:11]
	s_setprio 0
	s_barrier
	s_add_u32 s62, s30, 0x80000
	s_addc_u32 s63, s31, 0
	s_add_i32 s61, s49, s38
	v_lshl_add_u64 v[144:145], s[62:63], 0, v[130:131]
	s_mov_b32 m0, s61
	s_nop 0
	global_load_lds_dwordx4 v[144:145], off
	v_lshl_add_u64 v[144:145], s[62:63], 0, v[134:135]
	s_add_i32 m0, s61, 0x2000
	s_nop 0
	global_load_lds_dwordx4 v[144:145], off
	s_waitcnt vmcnt(6)
	s_barrier
	s_setprio 1
	v_mfma_f32_16x16x32_bf16 v[52:55], v[204:207], v[172:175], v[52:55]
	v_mfma_f32_16x16x32_bf16 v[48:51], v[212:215], v[172:175], v[48:51]
	v_mfma_f32_16x16x32_bf16 v[36:39], v[204:207], v[180:183], v[36:39]
	v_mfma_f32_16x16x32_bf16 v[32:35], v[212:215], v[180:183], v[32:35]
	v_mfma_f32_16x16x32_bf16 v[20:23], v[204:207], v[188:191], v[20:23]
	v_mfma_f32_16x16x32_bf16 v[16:19], v[212:215], v[188:191], v[16:19]
	v_mfma_f32_16x16x32_bf16 v[4:7], v[204:207], v[196:199], v[4:7]
	v_mfma_f32_16x16x32_bf16 v[0:3], v[212:215], v[196:199], v[0:3]
	v_mfma_f32_16x16x32_bf16 v[52:55], v[208:211], v[176:179], v[52:55]
	v_mfma_f32_16x16x32_bf16 v[48:51], v[216:219], v[176:179], v[48:51]
	v_mfma_f32_16x16x32_bf16 v[36:39], v[208:211], v[184:187], v[36:39]
	v_mfma_f32_16x16x32_bf16 v[32:35], v[216:219], v[184:187], v[32:35]
	v_mfma_f32_16x16x32_bf16 v[20:23], v[208:211], v[192:195], v[20:23]
	v_mfma_f32_16x16x32_bf16 v[16:19], v[216:219], v[192:195], v[16:19]
	v_mfma_f32_16x16x32_bf16 v[4:7], v[208:211], v[200:203], v[4:7]
	v_mfma_f32_16x16x32_bf16 v[0:3], v[216:219], v[200:203], v[0:3]
	s_setprio 0
	s_add_i32 s61, 0, 0x18000
	v_add_u32_e32 v155, s61, v149
	s_barrier
	ds_read_b128 v[144:147], v155
	ds_read_b128 v[156:159], v155 offset:1024
	ds_read_b128 v[160:163], v155 offset:2048
	ds_read_b128 v[164:167], v155 offset:3072
	s_add_u32 s34, s34, 0x80000
	s_addc_u32 s35, s35, 0
	s_mov_b32 m0, s41
	v_lshl_add_u64 v[204:205], s[34:35], 0, v[128:129]
	ds_read_b128 v[172:175], v152 offset:32768
	ds_read_b128 v[176:179], v152 offset:33792
	ds_read_b128 v[180:183], v152 offset:34816
	ds_read_b128 v[184:187], v152 offset:35840
	ds_read_b128 v[188:191], v152 offset:36864
	ds_read_b128 v[192:195], v152 offset:37888
	ds_read_b128 v[196:199], v152 offset:38912
	ds_read_b128 v[200:203], v152 offset:39936
	global_load_lds_dwordx4 v[204:205], off
	v_lshl_add_u64 v[204:205], s[34:35], 0, v[132:133]
	s_mov_b32 m0, s42
	s_nop 0
	global_load_lds_dwordx4 v[204:205], off
	s_waitcnt lgkmcnt(8)
	s_barrier
	s_waitcnt lgkmcnt(0)
	s_setprio 1
	s_waitcnt lgkmcnt(0)
	v_mfma_f32_16x16x32_bf16 v[124:127], v[144:147], v[172:175], v[124:127]
	v_mfma_f32_16x16x32_bf16 v[120:123], v[160:163], v[172:175], v[120:123]
	v_mfma_f32_16x16x32_bf16 v[108:111], v[144:147], v[180:183], v[108:111]
	v_mfma_f32_16x16x32_bf16 v[104:107], v[160:163], v[180:183], v[104:107]
	v_mfma_f32_16x16x32_bf16 v[92:95], v[144:147], v[188:191], v[92:95]
	v_mfma_f32_16x16x32_bf16 v[88:91], v[160:163], v[188:191], v[88:91]
	v_mfma_f32_16x16x32_bf16 v[76:79], v[144:147], v[196:199], v[76:79]
	v_mfma_f32_16x16x32_bf16 v[72:75], v[160:163], v[196:199], v[72:75]
	v_mfma_f32_16x16x32_bf16 v[124:127], v[156:159], v[176:179], v[124:127]
	v_mfma_f32_16x16x32_bf16 v[120:123], v[164:167], v[176:179], v[120:123]
	v_mfma_f32_16x16x32_bf16 v[108:111], v[156:159], v[184:187], v[108:111]
	v_mfma_f32_16x16x32_bf16 v[104:107], v[164:167], v[184:187], v[104:107]
	v_mfma_f32_16x16x32_bf16 v[92:95], v[156:159], v[192:195], v[92:95]
	v_mfma_f32_16x16x32_bf16 v[88:91], v[164:167], v[192:195], v[88:91]
	v_mfma_f32_16x16x32_bf16 v[76:79], v[156:159], v[200:203], v[76:79]
	v_mfma_f32_16x16x32_bf16 v[72:75], v[164:167], v[200:203], v[72:75]
	s_setprio 0
	s_barrier
	s_add_i32 s34, 0, 0x1c000
	s_add_i32 s35, s61, s38
	v_add_u32_e32 v155, s34, v149
	v_lshl_add_u64 v[168:169], v[168:169], 0, s[12:13]
	s_mov_b32 m0, s35
	ds_read_b128 v[204:207], v155
	ds_read_b128 v[208:211], v155 offset:1024
	ds_read_b128 v[212:215], v155 offset:2048
	ds_read_b128 v[216:219], v155 offset:3072
	global_load_lds_dwordx4 v[168:169], off
	v_lshl_add_u64 v[168:169], v[220:221], 0, s[12:13]
	s_add_i32 m0, s35, 0x2000
	s_nop 0
	global_load_lds_dwordx4 v[168:169], off
	s_barrier
	s_waitcnt lgkmcnt(0)
	s_setprio 1
	s_waitcnt lgkmcnt(0)
	v_mfma_f32_16x16x32_bf16 v[116:119], v[204:207], v[172:175], v[116:119]
	v_mfma_f32_16x16x32_bf16 v[112:115], v[212:215], v[172:175], v[112:115]
	v_mfma_f32_16x16x32_bf16 v[100:103], v[204:207], v[180:183], v[100:103]
	v_mfma_f32_16x16x32_bf16 v[96:99], v[212:215], v[180:183], v[96:99]
	v_mfma_f32_16x16x32_bf16 v[84:87], v[204:207], v[188:191], v[84:87]
	v_mfma_f32_16x16x32_bf16 v[80:83], v[212:215], v[188:191], v[80:83]
	v_mfma_f32_16x16x32_bf16 v[68:71], v[204:207], v[196:199], v[68:71]
	v_mfma_f32_16x16x32_bf16 v[64:67], v[212:215], v[196:199], v[64:67]
	v_mfma_f32_16x16x32_bf16 v[116:119], v[208:211], v[176:179], v[116:119]
	v_mfma_f32_16x16x32_bf16 v[112:115], v[216:219], v[176:179], v[112:115]
	v_mfma_f32_16x16x32_bf16 v[100:103], v[208:211], v[184:187], v[100:103]
	v_mfma_f32_16x16x32_bf16 v[96:99], v[216:219], v[184:187], v[96:99]
	v_mfma_f32_16x16x32_bf16 v[84:87], v[208:211], v[192:195], v[84:87]
	v_mfma_f32_16x16x32_bf16 v[80:83], v[216:219], v[192:195], v[80:83]
	v_mfma_f32_16x16x32_bf16 v[68:71], v[208:211], v[200:203], v[68:71]
	v_mfma_f32_16x16x32_bf16 v[64:67], v[216:219], v[200:203], v[64:67]
	s_setprio 0
	s_mov_b32 m0, s45
	v_lshl_add_u64 v[168:169], v[222:223], 0, s[12:13]
	s_barrier
	ds_read_b128 v[172:175], v152 offset:49152
	ds_read_b128 v[176:179], v152 offset:50176
	ds_read_b128 v[180:183], v152 offset:51200
	ds_read_b128 v[184:187], v152 offset:52224
	ds_read_b128 v[188:191], v152 offset:53248
	ds_read_b128 v[192:195], v152 offset:54272
	ds_read_b128 v[196:199], v152 offset:55296
	ds_read_b128 v[200:203], v152 offset:56320
	global_load_lds_dwordx4 v[168:169], off
	v_lshl_add_u64 v[168:169], v[224:225], 0, s[12:13]
	s_mov_b32 m0, s46
	s_nop 0
	global_load_lds_dwordx4 v[168:169], off
	s_barrier
	s_waitcnt lgkmcnt(0)
	s_setprio 1
	s_waitcnt lgkmcnt(0)
	v_mfma_f32_16x16x32_bf16 v[60:63], v[144:147], v[172:175], v[60:63]
	v_mfma_f32_16x16x32_bf16 v[56:59], v[160:163], v[172:175], v[56:59]
	v_mfma_f32_16x16x32_bf16 v[44:47], v[144:147], v[180:183], v[44:47]
	v_mfma_f32_16x16x32_bf16 v[40:43], v[160:163], v[180:183], v[40:43]
	v_mfma_f32_16x16x32_bf16 v[28:31], v[144:147], v[188:191], v[28:31]
	v_mfma_f32_16x16x32_bf16 v[24:27], v[160:163], v[188:191], v[24:27]
	v_mfma_f32_16x16x32_bf16 v[12:15], v[144:147], v[196:199], v[12:15]
	v_mfma_f32_16x16x32_bf16 v[8:11], v[160:163], v[196:199], v[8:11]
	v_mfma_f32_16x16x32_bf16 v[60:63], v[156:159], v[176:179], v[60:63]
	v_mfma_f32_16x16x32_bf16 v[56:59], v[164:167], v[176:179], v[56:59]
	v_mfma_f32_16x16x32_bf16 v[44:47], v[156:159], v[184:187], v[44:47]
	v_mfma_f32_16x16x32_bf16 v[40:43], v[164:167], v[184:187], v[40:43]
	v_mfma_f32_16x16x32_bf16 v[28:31], v[156:159], v[192:195], v[28:31]
	v_mfma_f32_16x16x32_bf16 v[24:27], v[164:167], v[192:195], v[24:27]
	v_mfma_f32_16x16x32_bf16 v[12:15], v[156:159], v[200:203], v[12:15]
	v_mfma_f32_16x16x32_bf16 v[8:11], v[164:167], v[200:203], v[8:11]
	s_setprio 0
	s_barrier
	s_add_u32 s30, s30, 0x80080
	s_addc_u32 s31, s31, 0
	s_add_i32 s34, s34, s38
	v_lshl_add_u64 v[144:145], s[30:31], 0, v[130:131]
	s_mov_b32 m0, s34
	s_nop 0
	global_load_lds_dwordx4 v[144:145], off
	v_lshl_add_u64 v[144:145], s[30:31], 0, v[134:135]
	s_add_i32 m0, s34, 0x2000
	s_nop 0
	global_load_lds_dwordx4 v[144:145], off
	s_waitcnt vmcnt(6)
	s_barrier
	s_setprio 1
	v_mfma_f32_16x16x32_bf16 v[52:55], v[204:207], v[172:175], v[52:55]
	v_mfma_f32_16x16x32_bf16 v[48:51], v[212:215], v[172:175], v[48:51]
	v_mfma_f32_16x16x32_bf16 v[36:39], v[204:207], v[180:183], v[36:39]
	v_mfma_f32_16x16x32_bf16 v[32:35], v[212:215], v[180:183], v[32:35]
	v_mfma_f32_16x16x32_bf16 v[20:23], v[204:207], v[188:191], v[20:23]
	v_mfma_f32_16x16x32_bf16 v[16:19], v[212:215], v[188:191], v[16:19]
	v_mfma_f32_16x16x32_bf16 v[4:7], v[204:207], v[196:199], v[4:7]
	v_mfma_f32_16x16x32_bf16 v[0:3], v[212:215], v[196:199], v[0:3]
	v_mfma_f32_16x16x32_bf16 v[52:55], v[208:211], v[176:179], v[52:55]
	v_mfma_f32_16x16x32_bf16 v[48:51], v[216:219], v[176:179], v[48:51]
	v_mfma_f32_16x16x32_bf16 v[36:39], v[208:211], v[184:187], v[36:39]
	v_mfma_f32_16x16x32_bf16 v[32:35], v[216:219], v[184:187], v[32:35]
	v_mfma_f32_16x16x32_bf16 v[20:23], v[208:211], v[192:195], v[20:23]
	v_mfma_f32_16x16x32_bf16 v[16:19], v[216:219], v[192:195], v[16:19]
	v_mfma_f32_16x16x32_bf16 v[4:7], v[208:211], v[200:203], v[4:7]
	v_mfma_f32_16x16x32_bf16 v[0:3], v[216:219], v[200:203], v[0:3]
	s_setprio 0
	s_add_i32 s60, s60, 2
	s_add_u32 s0, s0, 0x100
	s_addc_u32 s1, s1, 0
	s_add_u32 s58, s58, 0x100
	s_addc_u32 s59, s59, 0
	s_cmp_gt_u32 s60, 29
	s_barrier
	s_cbranch_scc0 .LBB0_1039
	v_lshl_add_u32 v156, s28, 8, v148
	v_ashrrev_i32_e32 v157, 31, v156
	v_lshl_add_u64 v[144:145], v[156:157], 2, s[8:9]
	v_lshl_or_b32 v146, s55, 8, v150
	v_ashrrev_i32_e32 v147, 31, v146
	v_lshlrev_b64 v[162:163], 1, v[146:147]
	v_lshlrev_b64 v[160:161], 12, v[156:157]
	v_readlane_b32 s0, v234, 9
	v_readlane_b32 s1, v234, 10
	v_or_b32_e32 v158, 16, v156
	v_ashrrev_i32_e32 v159, 31, v158
	s_mov_b32 s55, s20
	s_mov_b32 s28, s22
	s_mov_b64 s[30:31], s[26:27]
	s_mov_b64 s[34:35], s[24:25]
	v_fmamk_f32 v146, v236, 0x3a000000, v154
	v_mul_f32_e32 v147, 0x4b800000, v146
	v_cmp_gt_f32_e32 vcc, s50, v146
	s_nop 1
	v_cndmask_b32_e32 v146, v146, v147, vcc
	v_rsq_f32_e32 v155, v146
	v_lshl_add_u64 v[146:147], s[0:1], 0, v[160:161]
	v_lshl_add_u64 v[146:147], v[146:147], 0, v[162:163]
	v_lshl_add_u64 v[160:161], v[158:159], 2, s[8:9]
	v_mul_f32_e32 v157, 0x45800000, v155
	v_cndmask_b32_e32 v164, v155, v157, vcc
	v_pk_mul_f32 v[126:127], v[126:127], v[164:165] op_sel_hi:[1,0]
	v_pk_mul_f32 v[124:125], v[124:125], v[164:165] op_sel_hi:[1,0]
	v_pk_mul_f32 v[122:123], v[122:123], v[164:165] op_sel_hi:[1,0]
	v_pk_mul_f32 v[120:121], v[120:121], v[164:165] op_sel_hi:[1,0]
	v_pk_mul_f32 v[118:119], v[118:119], v[164:165] op_sel_hi:[1,0]
	v_pk_mul_f32 v[116:117], v[116:117], v[164:165] op_sel_hi:[1,0]
	v_pk_mul_f32 v[166:167], v[114:115], v[164:165] op_sel_hi:[1,0]
	v_pk_mul_f32 v[164:165], v[112:113], v[164:165] op_sel_hi:[1,0]
	v_cvt_pk_bf16_f32 v112, v124, v125
	v_cvt_pk_bf16_f32 v113, v126, v127
	v_cvt_pk_bf16_f32 v114, v120, v121
	v_cvt_pk_bf16_f32 v115, v122, v123
	v_cvt_pk_bf16_f32 v116, v116, v117
	v_cvt_pk_bf16_f32 v117, v118, v119
	v_cvt_pk_bf16_f32 v118, v164, v165
	v_cvt_pk_bf16_f32 v119, v166, v167
	global_store_dwordx4 v[146:147], v[112:115], off
	global_store_dwordx4 v[146:147], v[116:119], off offset:256
	v_lshlrev_b64 v[114:115], 12, v[158:159]
	v_or_b32_e32 v112, 32, v156
	v_lshl_add_u64 v[114:115], s[0:1], 0, v[114:115]
	v_ashrrev_i32_e32 v113, 31, v112
	v_lshl_add_u64 v[114:115], v[114:115], 0, v[162:163]
	v_fmamk_f32 v116, v237, 0x3a000000, v154
	v_mul_f32_e32 v117, 0x4b800000, v116
	v_cmp_gt_f32_e32 vcc, s50, v116
	s_nop 1
	v_cndmask_b32_e32 v116, v116, v117, vcc
	v_rsq_f32_e32 v118, v116
	v_lshl_add_u64 v[116:117], v[112:113], 2, s[8:9]
	v_mul_f32_e32 v119, 0x45800000, v118
	v_cndmask_b32_e32 v118, v118, v119, vcc
	v_pk_mul_f32 v[110:111], v[110:111], v[118:119] op_sel_hi:[1,0]
	v_pk_mul_f32 v[108:109], v[108:109], v[118:119] op_sel_hi:[1,0]
	v_pk_mul_f32 v[106:107], v[106:107], v[118:119] op_sel_hi:[1,0]
	v_pk_mul_f32 v[104:105], v[104:105], v[118:119] op_sel_hi:[1,0]
	v_pk_mul_f32 v[102:103], v[102:103], v[118:119] op_sel_hi:[1,0]
	v_pk_mul_f32 v[100:101], v[100:101], v[118:119] op_sel_hi:[1,0]
	v_pk_mul_f32 v[120:121], v[98:99], v[118:119] op_sel_hi:[1,0]
	v_pk_mul_f32 v[118:119], v[96:97], v[118:119] op_sel_hi:[1,0]
	v_cvt_pk_bf16_f32 v96, v108, v109
	v_cvt_pk_bf16_f32 v97, v110, v111
	v_cvt_pk_bf16_f32 v98, v104, v105
	v_cvt_pk_bf16_f32 v99, v106, v107
	v_cvt_pk_bf16_f32 v100, v100, v101
	v_cvt_pk_bf16_f32 v101, v102, v103
	v_cvt_pk_bf16_f32 v102, v118, v119
	v_cvt_pk_bf16_f32 v103, v120, v121
	global_store_dwordx4 v[114:115], v[96:99], off
	global_store_dwordx4 v[114:115], v[100:103], off offset:256
	v_lshlrev_b64 v[98:99], 12, v[112:113]
	v_or_b32_e32 v96, 48, v156
	v_lshl_add_u64 v[98:99], s[0:1], 0, v[98:99]
	v_ashrrev_i32_e32 v97, 31, v96
	v_lshl_add_u64 v[98:99], v[98:99], 0, v[162:163]
	v_fmamk_f32 v100, v238, 0x3a000000, v154
	v_mul_f32_e32 v101, 0x4b800000, v100
	v_cmp_gt_f32_e32 vcc, s50, v100
	s_nop 1
	v_cndmask_b32_e32 v100, v100, v101, vcc
	v_rsq_f32_e32 v102, v100
	v_lshl_add_u64 v[100:101], v[96:97], 2, s[8:9]
	v_mul_f32_e32 v103, 0x45800000, v102
	v_cndmask_b32_e32 v102, v102, v103, vcc
	v_pk_mul_f32 v[94:95], v[94:95], v[102:103] op_sel_hi:[1,0]
	v_pk_mul_f32 v[92:93], v[92:93], v[102:103] op_sel_hi:[1,0]
	v_pk_mul_f32 v[90:91], v[90:91], v[102:103] op_sel_hi:[1,0]
	v_pk_mul_f32 v[88:89], v[88:89], v[102:103] op_sel_hi:[1,0]
	v_pk_mul_f32 v[86:87], v[86:87], v[102:103] op_sel_hi:[1,0]
	v_pk_mul_f32 v[84:85], v[84:85], v[102:103] op_sel_hi:[1,0]
	v_pk_mul_f32 v[104:105], v[82:83], v[102:103] op_sel_hi:[1,0]
	v_pk_mul_f32 v[102:103], v[80:81], v[102:103] op_sel_hi:[1,0]
	v_cvt_pk_bf16_f32 v80, v92, v93
	v_cvt_pk_bf16_f32 v81, v94, v95
	v_cvt_pk_bf16_f32 v82, v88, v89
	v_cvt_pk_bf16_f32 v83, v90, v91
	v_cvt_pk_bf16_f32 v84, v84, v85
	v_cvt_pk_bf16_f32 v85, v86, v87
	v_cvt_pk_bf16_f32 v86, v102, v103
	v_cvt_pk_bf16_f32 v87, v104, v105
	global_store_dwordx4 v[98:99], v[80:83], off
	global_store_dwordx4 v[98:99], v[84:87], off offset:256
	v_fmamk_f32 v80, v239, 0x3a000000, v154
	v_mul_f32_e32 v81, 0x4b800000, v80
	v_cmp_gt_f32_e32 vcc, s50, v80
	s_nop 1
	v_cndmask_b32_e32 v80, v80, v81, vcc
	v_rsq_f32_e32 v82, v80
	v_lshlrev_b64 v[80:81], 12, v[96:97]
	v_lshl_add_u64 v[80:81], s[0:1], 0, v[80:81]
	v_lshl_add_u64 v[80:81], v[80:81], 0, v[162:163]
	v_mul_f32_e32 v83, 0x45800000, v82
	v_cndmask_b32_e32 v82, v82, v83, vcc
	v_pk_mul_f32 v[78:79], v[78:79], v[82:83] op_sel_hi:[1,0]
	v_pk_mul_f32 v[76:77], v[76:77], v[82:83] op_sel_hi:[1,0]
	v_pk_mul_f32 v[74:75], v[74:75], v[82:83] op_sel_hi:[1,0]
	v_pk_mul_f32 v[72:73], v[72:73], v[82:83] op_sel_hi:[1,0]
	v_pk_mul_f32 v[70:71], v[70:71], v[82:83] op_sel_hi:[1,0]
	v_pk_mul_f32 v[68:69], v[68:69], v[82:83] op_sel_hi:[1,0]
	v_pk_mul_f32 v[84:85], v[66:67], v[82:83] op_sel_hi:[1,0]
	v_pk_mul_f32 v[82:83], v[64:65], v[82:83] op_sel_hi:[1,0]
	v_cvt_pk_bf16_f32 v64, v76, v77
	v_cvt_pk_bf16_f32 v65, v78, v79
	v_cvt_pk_bf16_f32 v66, v72, v73
	v_cvt_pk_bf16_f32 v67, v74, v75
	v_cvt_pk_bf16_f32 v68, v68, v69
	v_cvt_pk_bf16_f32 v69, v70, v71
	v_cvt_pk_bf16_f32 v70, v82, v83
	v_cvt_pk_bf16_f32 v71, v84, v85
	global_store_dwordx4 v[80:81], v[64:67], off
	global_store_dwordx4 v[80:81], v[68:71], off offset:256
	v_lshl_add_u64 v[64:65], v[146:147], 0, s[10:11]
	v_fmamk_f32 v66, v240, 0x3a000000, v154
	v_mul_f32_e32 v67, 0x4b800000, v66
	v_cmp_gt_f32_e32 vcc, s50, v66
	s_nop 1
	v_cndmask_b32_e32 v66, v66, v67, vcc
	v_rsq_f32_e32 v68, v66
	v_add_co_u32_e64 v66, s[0:1], s51, v146
	v_mul_f32_e32 v69, 0x45800000, v68
	v_cndmask_b32_e32 v68, v68, v69, vcc
	v_pk_mul_f32 v[62:63], v[62:63], v[68:69] op_sel_hi:[1,0]
	v_pk_mul_f32 v[60:61], v[60:61], v[68:69] op_sel_hi:[1,0]
	v_pk_mul_f32 v[58:59], v[58:59], v[68:69] op_sel_hi:[1,0]
	v_pk_mul_f32 v[56:57], v[56:57], v[68:69] op_sel_hi:[1,0]
	v_addc_co_u32_e64 v67, s[0:1], 0, v147, s[0:1]
	v_pk_mul_f32 v[54:55], v[54:55], v[68:69] op_sel_hi:[1,0]
	v_pk_mul_f32 v[52:53], v[52:53], v[68:69] op_sel_hi:[1,0]
	v_pk_mul_f32 v[70:71], v[50:51], v[68:69] op_sel_hi:[1,0]
	v_pk_mul_f32 v[68:69], v[48:49], v[68:69] op_sel_hi:[1,0]
	v_cvt_pk_bf16_f32 v48, v60, v61
	v_cvt_pk_bf16_f32 v49, v62, v63
	v_cvt_pk_bf16_f32 v50, v56, v57
	v_cvt_pk_bf16_f32 v51, v58, v59
	v_cvt_pk_bf16_f32 v52, v52, v53
	v_cvt_pk_bf16_f32 v53, v54, v55
	v_cvt_pk_bf16_f32 v54, v68, v69
	v_cvt_pk_bf16_f32 v55, v70, v71
	global_store_dwordx4 v[66:67], v[48:51], off
	global_store_dwordx4 v[64:65], v[52:55], off offset:256
	v_lshl_add_u64 v[48:49], v[146:147], 0, s[14:15]
	v_fmamk_f32 v50, v241, 0x3a000000, v154
	v_mul_f32_e32 v51, 0x4b800000, v50
	v_cmp_gt_f32_e32 vcc, s50, v50
	s_nop 1
	v_cndmask_b32_e32 v50, v50, v51, vcc
	v_rsq_f32_e32 v52, v50
	v_add_co_u32_e64 v50, s[0:1], s52, v146
	v_mul_f32_e32 v53, 0x45800000, v52
	v_cndmask_b32_e32 v52, v52, v53, vcc
	v_pk_mul_f32 v[46:47], v[46:47], v[52:53] op_sel_hi:[1,0]
	v_pk_mul_f32 v[44:45], v[44:45], v[52:53] op_sel_hi:[1,0]
	v_pk_mul_f32 v[42:43], v[42:43], v[52:53] op_sel_hi:[1,0]
	v_pk_mul_f32 v[40:41], v[40:41], v[52:53] op_sel_hi:[1,0]
	v_addc_co_u32_e64 v51, s[0:1], 0, v147, s[0:1]
	v_pk_mul_f32 v[38:39], v[38:39], v[52:53] op_sel_hi:[1,0]
	v_pk_mul_f32 v[36:37], v[36:37], v[52:53] op_sel_hi:[1,0]
	v_pk_mul_f32 v[54:55], v[34:35], v[52:53] op_sel_hi:[1,0]
	v_pk_mul_f32 v[52:53], v[32:33], v[52:53] op_sel_hi:[1,0]
	v_cvt_pk_bf16_f32 v32, v44, v45
	v_cvt_pk_bf16_f32 v33, v46, v47
	v_cvt_pk_bf16_f32 v34, v40, v41
	v_cvt_pk_bf16_f32 v35, v42, v43
	v_cvt_pk_bf16_f32 v36, v36, v37
	v_cvt_pk_bf16_f32 v37, v38, v39
	v_cvt_pk_bf16_f32 v38, v52, v53
	v_cvt_pk_bf16_f32 v39, v54, v55
	global_store_dwordx4 v[50:51], v[32:35], off
	global_store_dwordx4 v[48:49], v[36:39], off offset:256
	v_lshl_add_u64 v[32:33], v[146:147], 0, s[16:17]
	v_fmamk_f32 v34, v242, 0x3a000000, v154
	v_mul_f32_e32 v35, 0x4b800000, v34
	v_cmp_gt_f32_e32 vcc, s50, v34
	s_nop 1
	v_cndmask_b32_e32 v34, v34, v35, vcc
	v_rsq_f32_e32 v36, v34
	v_add_co_u32_e64 v34, s[0:1], s53, v146
	v_mul_f32_e32 v37, 0x45800000, v36
	v_cndmask_b32_e32 v36, v36, v37, vcc
	v_pk_mul_f32 v[30:31], v[30:31], v[36:37] op_sel_hi:[1,0]
	v_pk_mul_f32 v[28:29], v[28:29], v[36:37] op_sel_hi:[1,0]
	v_pk_mul_f32 v[26:27], v[26:27], v[36:37] op_sel_hi:[1,0]
	v_pk_mul_f32 v[24:25], v[24:25], v[36:37] op_sel_hi:[1,0]
	v_addc_co_u32_e64 v35, s[0:1], 0, v147, s[0:1]
	v_pk_mul_f32 v[22:23], v[22:23], v[36:37] op_sel_hi:[1,0]
	v_pk_mul_f32 v[20:21], v[20:21], v[36:37] op_sel_hi:[1,0]
	v_pk_mul_f32 v[38:39], v[18:19], v[36:37] op_sel_hi:[1,0]
	v_pk_mul_f32 v[36:37], v[16:17], v[36:37] op_sel_hi:[1,0]
	v_cvt_pk_bf16_f32 v16, v28, v29
	v_cvt_pk_bf16_f32 v17, v30, v31
	v_cvt_pk_bf16_f32 v18, v24, v25
	v_cvt_pk_bf16_f32 v19, v26, v27
	v_cvt_pk_bf16_f32 v20, v20, v21
	v_cvt_pk_bf16_f32 v21, v22, v23
	v_cvt_pk_bf16_f32 v22, v36, v37
	v_cvt_pk_bf16_f32 v23, v38, v39
	global_store_dwordx4 v[34:35], v[16:19], off
	global_store_dwordx4 v[32:33], v[20:23], off offset:256
	s_and_b64 vcc, exec, s[2:3]
	v_lshl_add_u64 v[16:17], v[146:147], 0, s[18:19]
	v_fmamk_f32 v18, v243, 0x3a000000, v154
	v_mul_f32_e32 v19, 0x4b800000, v18
	v_cmp_gt_f32_e64 s[0:1], s50, v18
	s_nop 1
	v_cndmask_b32_e64 v18, v18, v19, s[0:1]
	v_rsq_f32_e32 v20, v18
	v_add_co_u32_e64 v18, s[2:3], s54, v146
	v_mul_f32_e32 v21, 0x45800000, v20
	v_cndmask_b32_e64 v20, v20, v21, s[0:1]
	v_pk_mul_f32 v[14:15], v[14:15], v[20:21] op_sel_hi:[1,0]
	v_pk_mul_f32 v[12:13], v[12:13], v[20:21] op_sel_hi:[1,0]
	v_pk_mul_f32 v[10:11], v[10:11], v[20:21] op_sel_hi:[1,0]
	v_pk_mul_f32 v[8:9], v[8:9], v[20:21] op_sel_hi:[1,0]
	v_addc_co_u32_e64 v19, s[2:3], 0, v147, s[2:3]
	v_pk_mul_f32 v[6:7], v[6:7], v[20:21] op_sel_hi:[1,0]
	v_pk_mul_f32 v[4:5], v[4:5], v[20:21] op_sel_hi:[1,0]
	v_pk_mul_f32 v[22:23], v[2:3], v[20:21] op_sel_hi:[1,0]
	v_pk_mul_f32 v[20:21], v[0:1], v[20:21] op_sel_hi:[1,0]
	v_cvt_pk_bf16_f32 v0, v12, v13
	v_cvt_pk_bf16_f32 v1, v14, v15
	v_cvt_pk_bf16_f32 v2, v8, v9
	v_cvt_pk_bf16_f32 v3, v10, v11
	v_cvt_pk_bf16_f32 v4, v4, v5
	v_cvt_pk_bf16_f32 v5, v6, v7
	v_cvt_pk_bf16_f32 v6, v20, v21
	v_cvt_pk_bf16_f32 v7, v22, v23
	global_store_dwordx4 v[18:19], v[0:3], off
	global_store_dwordx4 v[16:17], v[4:7], off offset:256
	s_cbranch_vccz .LBB0_1032
	s_waitcnt vmcnt(0)
	s_cmpk_gt_u32 s33, 0xff
	s_cbranch_scc1 .LBB0_1043
	s_barrier

.LBB0_1270:
	s_ashr_i32 s23, s22, 31
	v_cmp_lt_i64_e32 vcc, s[0:1], v[140:141]
	s_lshl_b64 s[0:1], s[22:23], 20
	s_add_u32 s24, s6, s0
	s_addc_u32 s25, s7, s1
	s_and_b64 s[0:1], vcc, exec
	s_cselect_b32 s23, s25, s35
	s_cselect_b32 s56, s24, s34
	s_ashr_i32 s21, s20, 31
	s_lshl_b64 s[0:1], s[20:21], 20
	s_add_u32 s26, s36, s0
	s_addc_u32 s27, s37, s1
	s_and_b64 s[0:1], vcc, exec
	s_cselect_b32 s21, s27, s31
	s_cselect_b32 s57, s26, s30
	s_add_u32 s0, s34, 0x80080
	s_addc_u32 s1, s35, 0
	s_add_u32 s58, s30, 0x100
	v_mov_b32_e32 v0, 0
	s_addc_u32 s59, s31, 0
	s_mov_b32 s60, -2
	v_mov_b32_e32 v1, v0
	v_mov_b32_e32 v2, v0
	v_mov_b32_e32 v3, v0
	v_mov_b32_e32 v4, v0
	v_mov_b32_e32 v5, v0
	v_mov_b32_e32 v6, v0
	v_mov_b32_e32 v7, v0
	v_mov_b32_e32 v16, v0
	v_mov_b32_e32 v17, v0
	v_mov_b32_e32 v18, v0
	v_mov_b32_e32 v19, v0
	v_mov_b32_e32 v20, v0
	v_mov_b32_e32 v21, v0
	v_mov_b32_e32 v22, v0
	v_mov_b32_e32 v23, v0
	v_mov_b32_e32 v32, v0
	v_mov_b32_e32 v33, v0
	v_mov_b32_e32 v34, v0
	v_mov_b32_e32 v35, v0
	v_mov_b32_e32 v36, v0
	v_mov_b32_e32 v37, v0
	v_mov_b32_e32 v38, v0
	v_mov_b32_e32 v39, v0
	v_mov_b32_e32 v48, v0
	v_mov_b32_e32 v49, v0
	v_mov_b32_e32 v50, v0
	v_mov_b32_e32 v51, v0
	v_mov_b32_e32 v52, v0
	v_mov_b32_e32 v53, v0
	v_mov_b32_e32 v54, v0
	v_mov_b32_e32 v55, v0
	v_mov_b32_e32 v8, v0
	v_mov_b32_e32 v9, v0
	v_mov_b32_e32 v10, v0
	v_mov_b32_e32 v11, v0
	v_mov_b32_e32 v12, v0
	v_mov_b32_e32 v13, v0
	v_mov_b32_e32 v14, v0
	v_mov_b32_e32 v15, v0
	v_mov_b32_e32 v24, v0
	v_mov_b32_e32 v25, v0
	v_mov_b32_e32 v26, v0
	v_mov_b32_e32 v27, v0
	v_mov_b32_e32 v28, v0
	v_mov_b32_e32 v29, v0
	v_mov_b32_e32 v30, v0
	v_mov_b32_e32 v31, v0
	v_mov_b32_e32 v40, v0
	v_mov_b32_e32 v41, v0
	v_mov_b32_e32 v42, v0
	v_mov_b32_e32 v43, v0
	v_mov_b32_e32 v44, v0
	v_mov_b32_e32 v45, v0
	v_mov_b32_e32 v46, v0
	v_mov_b32_e32 v47, v0
	v_mov_b32_e32 v56, v0
	v_mov_b32_e32 v57, v0
	v_mov_b32_e32 v58, v0
	v_mov_b32_e32 v59, v0
	v_mov_b32_e32 v60, v0
	v_mov_b32_e32 v61, v0
	v_mov_b32_e32 v62, v0
	v_mov_b32_e32 v63, v0
	v_mov_b32_e32 v64, v0
	v_mov_b32_e32 v65, v0
	v_mov_b32_e32 v66, v0
	v_mov_b32_e32 v67, v0
	v_mov_b32_e32 v68, v0
	v_mov_b32_e32 v69, v0
	v_mov_b32_e32 v70, v0
	v_mov_b32_e32 v71, v0
	v_mov_b32_e32 v80, v0
	v_mov_b32_e32 v81, v0
	v_mov_b32_e32 v82, v0
	v_mov_b32_e32 v83, v0
	v_mov_b32_e32 v84, v0
	v_mov_b32_e32 v85, v0
	v_mov_b32_e32 v86, v0
	v_mov_b32_e32 v87, v0
	v_mov_b32_e32 v96, v0
	v_mov_b32_e32 v97, v0
	v_mov_b32_e32 v98, v0
	v_mov_b32_e32 v99, v0
	v_mov_b32_e32 v100, v0
	v_mov_b32_e32 v101, v0
	v_mov_b32_e32 v102, v0
	v_mov_b32_e32 v103, v0
	v_mov_b32_e32 v112, v0
	v_mov_b32_e32 v113, v0
	v_mov_b32_e32 v114, v0
	v_mov_b32_e32 v115, v0
	v_mov_b32_e32 v116, v0
	v_mov_b32_e32 v117, v0
	v_mov_b32_e32 v118, v0
	v_mov_b32_e32 v119, v0
	v_mov_b32_e32 v72, v0
	v_mov_b32_e32 v73, v0
	v_mov_b32_e32 v74, v0
	v_mov_b32_e32 v75, v0
	v_mov_b32_e32 v76, v0
	v_mov_b32_e32 v77, v0
	v_mov_b32_e32 v78, v0
	v_mov_b32_e32 v79, v0
	v_mov_b32_e32 v88, v0
	v_mov_b32_e32 v89, v0
	v_mov_b32_e32 v90, v0
	v_mov_b32_e32 v91, v0
	v_mov_b32_e32 v92, v0
	v_mov_b32_e32 v93, v0
	v_mov_b32_e32 v94, v0
	v_mov_b32_e32 v95, v0
	v_mov_b32_e32 v104, v0
	v_mov_b32_e32 v105, v0
	v_mov_b32_e32 v106, v0
	v_mov_b32_e32 v107, v0
	v_mov_b32_e32 v108, v0
	v_mov_b32_e32 v109, v0
	v_mov_b32_e32 v110, v0
	v_mov_b32_e32 v111, v0
	v_mov_b32_e32 v120, v0
	v_mov_b32_e32 v121, v0
	v_mov_b32_e32 v122, v0
	v_mov_b32_e32 v123, v0
	v_mov_b32_e32 v124, v0
	v_mov_b32_e32 v125, v0
	v_mov_b32_e32 v126, v0
	v_mov_b32_e32 v127, v0
	v_lshl_add_u32 v252, s28, 8, v152
	v_ashrrev_i32_e32 v253, 31, v252
	v_lshl_add_u64 v[254:255], v[252:253], 2, s[8:9]
	global_load_dword v236, v[254:255], off
	global_load_dword v237, v[254:255], off offset:64
	global_load_dword v238, v[254:255], off offset:128
	global_load_dword v239, v[254:255], off offset:192
	global_load_dword v240, v[254:255], off offset:512
	global_load_dword v241, v[254:255], off offset:576
	global_load_dword v242, v[254:255], off offset:640
	global_load_dword v243, v[254:255], off offset:704
.LBB0_1271:
	ds_read_b128 v[144:147], v155
	ds_read_b128 v[148:151], v155 offset:1024
	ds_read_b128 v[160:163], v155 offset:2048
	ds_read_b128 v[164:167], v155 offset:3072
	s_add_u32 s30, s0, 0xfff80080
	s_addc_u32 s31, s1, -1
	s_cmp_eq_u32 s60, 28
	s_cselect_b32 s35, s23, s31
	s_cselect_b32 s34, s56, s30
	s_cselect_b32 s31, s21, s59
	s_cselect_b32 s30, s57, s58
	v_lshl_add_u64 v[168:169], s[0:1], 0, v[136:137]
	s_add_i32 m0, s29, 0xc000
	ds_read_b128 v[172:175], v156
	ds_read_b128 v[176:179], v156 offset:1024
	ds_read_b128 v[180:183], v156 offset:2048
	ds_read_b128 v[184:187], v156 offset:3072
	ds_read_b128 v[188:191], v156 offset:4096
	ds_read_b128 v[192:195], v156 offset:5120
	ds_read_b128 v[196:199], v156 offset:6144
	ds_read_b128 v[200:203], v156 offset:7168
	global_load_lds_dwordx4 v[168:169], off
	v_lshl_add_u64 v[168:169], s[0:1], 0, v[138:139]
	s_add_i32 m0, s29, 0xe000
	s_nop 0
	global_load_lds_dwordx4 v[168:169], off
	s_waitcnt lgkmcnt(8)
	s_barrier
	s_waitcnt lgkmcnt(0)
	s_setprio 1
	s_waitcnt lgkmcnt(0)
	v_mfma_f32_16x16x32_bf16 v[124:127], v[144:147], v[172:175], v[124:127]
	v_mfma_f32_16x16x32_bf16 v[120:123], v[160:163], v[172:175], v[120:123]
	v_mfma_f32_16x16x32_bf16 v[108:111], v[144:147], v[180:183], v[108:111]
	v_mfma_f32_16x16x32_bf16 v[104:107], v[160:163], v[180:183], v[104:107]
	v_mfma_f32_16x16x32_bf16 v[92:95], v[144:147], v[188:191], v[92:95]
	v_mfma_f32_16x16x32_bf16 v[88:91], v[160:163], v[188:191], v[88:91]
	v_mfma_f32_16x16x32_bf16 v[76:79], v[144:147], v[196:199], v[76:79]
	v_mfma_f32_16x16x32_bf16 v[72:75], v[160:163], v[196:199], v[72:75]
	v_mfma_f32_16x16x32_bf16 v[124:127], v[148:151], v[176:179], v[124:127]
	v_mfma_f32_16x16x32_bf16 v[120:123], v[164:167], v[176:179], v[120:123]
	v_mfma_f32_16x16x32_bf16 v[108:111], v[148:151], v[184:187], v[108:111]
	v_mfma_f32_16x16x32_bf16 v[104:107], v[164:167], v[184:187], v[104:107]
	v_mfma_f32_16x16x32_bf16 v[92:95], v[148:151], v[192:195], v[92:95]
	v_mfma_f32_16x16x32_bf16 v[88:91], v[164:167], v[192:195], v[88:91]
	v_mfma_f32_16x16x32_bf16 v[76:79], v[148:151], v[200:203], v[76:79]
	v_mfma_f32_16x16x32_bf16 v[72:75], v[164:167], v[200:203], v[72:75]
	s_setprio 0
	s_barrier
	s_add_i32 s61, s48, s38
	v_lshl_add_u64 v[168:169], s[30:31], 0, v[130:131]
	s_mov_b32 m0, s61
	ds_read_b128 v[204:207], v157
	ds_read_b128 v[208:211], v157 offset:1024
	ds_read_b128 v[212:215], v157 offset:2048
	ds_read_b128 v[216:219], v157 offset:3072
	global_load_lds_dwordx4 v[168:169], off
	v_lshl_add_u64 v[220:221], s[30:31], 0, v[134:135]
	s_add_i32 m0, s61, 0x2000
	s_nop 0
	global_load_lds_dwordx4 v[220:221], off
	s_barrier
	s_waitcnt lgkmcnt(0)
	s_setprio 1
	s_waitcnt lgkmcnt(0)
	v_mfma_f32_16x16x32_bf16 v[116:119], v[204:207], v[172:175], v[116:119]
	v_mfma_f32_16x16x32_bf16 v[112:115], v[212:215], v[172:175], v[112:115]
	v_mfma_f32_16x16x32_bf16 v[100:103], v[204:207], v[180:183], v[100:103]
	v_mfma_f32_16x16x32_bf16 v[96:99], v[212:215], v[180:183], v[96:99]
	v_mfma_f32_16x16x32_bf16 v[84:87], v[204:207], v[188:191], v[84:87]
	v_mfma_f32_16x16x32_bf16 v[80:83], v[212:215], v[188:191], v[80:83]
	v_mfma_f32_16x16x32_bf16 v[68:71], v[204:207], v[196:199], v[68:71]
	v_mfma_f32_16x16x32_bf16 v[64:67], v[212:215], v[196:199], v[64:67]
	v_mfma_f32_16x16x32_bf16 v[116:119], v[208:211], v[176:179], v[116:119]
	v_mfma_f32_16x16x32_bf16 v[112:115], v[216:219], v[176:179], v[112:115]
	v_mfma_f32_16x16x32_bf16 v[100:103], v[208:211], v[184:187], v[100:103]
	v_mfma_f32_16x16x32_bf16 v[96:99], v[216:219], v[184:187], v[96:99]
	v_mfma_f32_16x16x32_bf16 v[84:87], v[208:211], v[192:195], v[84:87]
	v_mfma_f32_16x16x32_bf16 v[80:83], v[216:219], v[192:195], v[80:83]
	v_mfma_f32_16x16x32_bf16 v[68:71], v[208:211], v[200:203], v[68:71]
	v_mfma_f32_16x16x32_bf16 v[64:67], v[216:219], v[200:203], v[64:67]
	s_setprio 0
	s_mov_b32 m0, s29
	v_lshl_add_u64 v[222:223], s[34:35], 0, v[128:129]
	s_barrier
	ds_read_b128 v[172:175], v156 offset:16384
	ds_read_b128 v[176:179], v156 offset:17408
	ds_read_b128 v[180:183], v156 offset:18432
	ds_read_b128 v[184:187], v156 offset:19456
	ds_read_b128 v[188:191], v156 offset:20480
	ds_read_b128 v[192:195], v156 offset:21504
	ds_read_b128 v[196:199], v156 offset:22528
	ds_read_b128 v[200:203], v156 offset:23552
	global_load_lds_dwordx4 v[222:223], off
	v_lshl_add_u64 v[224:225], s[34:35], 0, v[132:133]
	s_mov_b32 m0, s40
	s_nop 0
	global_load_lds_dwordx4 v[224:225], off
	s_barrier
	s_waitcnt lgkmcnt(0)
	s_setprio 1
	s_waitcnt lgkmcnt(0)
	v_mfma_f32_16x16x32_bf16 v[60:63], v[144:147], v[172:175], v[60:63]
	v_mfma_f32_16x16x32_bf16 v[56:59], v[160:163], v[172:175], v[56:59]
	v_mfma_f32_16x16x32_bf16 v[44:47], v[144:147], v[180:183], v[44:47]
	v_mfma_f32_16x16x32_bf16 v[40:43], v[160:163], v[180:183], v[40:43]
	v_mfma_f32_16x16x32_bf16 v[28:31], v[144:147], v[188:191], v[28:31]
	v_mfma_f32_16x16x32_bf16 v[24:27], v[160:163], v[188:191], v[24:27]
	v_mfma_f32_16x16x32_bf16 v[12:15], v[144:147], v[196:199], v[12:15]
	v_mfma_f32_16x16x32_bf16 v[8:11], v[160:163], v[196:199], v[8:11]
	v_mfma_f32_16x16x32_bf16 v[60:63], v[148:151], v[176:179], v[60:63]
	v_mfma_f32_16x16x32_bf16 v[56:59], v[164:167], v[176:179], v[56:59]
	v_mfma_f32_16x16x32_bf16 v[44:47], v[148:151], v[184:187], v[44:47]
	v_mfma_f32_16x16x32_bf16 v[40:43], v[164:167], v[184:187], v[40:43]
	v_mfma_f32_16x16x32_bf16 v[28:31], v[148:151], v[192:195], v[28:31]
	v_mfma_f32_16x16x32_bf16 v[24:27], v[164:167], v[192:195], v[24:27]
	v_mfma_f32_16x16x32_bf16 v[12:15], v[148:151], v[200:203], v[12:15]
	v_mfma_f32_16x16x32_bf16 v[8:11], v[164:167], v[200:203], v[8:11]
	s_setprio 0
	s_barrier
	s_add_u32 s62, s30, 0x80000
	s_addc_u32 s63, s31, 0
	s_add_i32 s61, s49, s38
	v_lshl_add_u64 v[144:145], s[62:63], 0, v[130:131]
	s_mov_b32 m0, s61
	s_nop 0
	global_load_lds_dwordx4 v[144:145], off
	v_lshl_add_u64 v[144:145], s[62:63], 0, v[134:135]
	s_add_i32 m0, s61, 0x2000
	s_nop 0
	global_load_lds_dwordx4 v[144:145], off
	s_waitcnt vmcnt(6)
	s_barrier
	s_setprio 1
	v_mfma_f32_16x16x32_bf16 v[52:55], v[204:207], v[172:175], v[52:55]
	v_mfma_f32_16x16x32_bf16 v[48:51], v[212:215], v[172:175], v[48:51]
	v_mfma_f32_16x16x32_bf16 v[36:39], v[204:207], v[180:183], v[36:39]
	v_mfma_f32_16x16x32_bf16 v[32:35], v[212:215], v[180:183], v[32:35]
	v_mfma_f32_16x16x32_bf16 v[20:23], v[204:207], v[188:191], v[20:23]
	v_mfma_f32_16x16x32_bf16 v[16:19], v[212:215], v[188:191], v[16:19]
	v_mfma_f32_16x16x32_bf16 v[4:7], v[204:207], v[196:199], v[4:7]
	v_mfma_f32_16x16x32_bf16 v[0:3], v[212:215], v[196:199], v[0:3]
	v_mfma_f32_16x16x32_bf16 v[52:55], v[208:211], v[176:179], v[52:55]
	v_mfma_f32_16x16x32_bf16 v[48:51], v[216:219], v[176:179], v[48:51]
	v_mfma_f32_16x16x32_bf16 v[36:39], v[208:211], v[184:187], v[36:39]
	v_mfma_f32_16x16x32_bf16 v[32:35], v[216:219], v[184:187], v[32:35]
	v_mfma_f32_16x16x32_bf16 v[20:23], v[208:211], v[192:195], v[20:23]
	v_mfma_f32_16x16x32_bf16 v[16:19], v[216:219], v[192:195], v[16:19]
	v_mfma_f32_16x16x32_bf16 v[4:7], v[208:211], v[200:203], v[4:7]
	v_mfma_f32_16x16x32_bf16 v[0:3], v[216:219], v[200:203], v[0:3]
	s_setprio 0
	s_add_i32 s61, 0, 0x18000
	v_add_u32_e32 v159, s61, v153
	s_barrier
	ds_read_b128 v[144:147], v159
	ds_read_b128 v[148:151], v159 offset:1024
	ds_read_b128 v[160:163], v159 offset:2048
	ds_read_b128 v[164:167], v159 offset:3072
	s_add_u32 s34, s34, 0x80000
	s_addc_u32 s35, s35, 0
	s_mov_b32 m0, s41
	v_lshl_add_u64 v[204:205], s[34:35], 0, v[128:129]
	ds_read_b128 v[172:175], v156 offset:32768
	ds_read_b128 v[176:179], v156 offset:33792
	ds_read_b128 v[180:183], v156 offset:34816
	ds_read_b128 v[184:187], v156 offset:35840
	ds_read_b128 v[188:191], v156 offset:36864
	ds_read_b128 v[192:195], v156 offset:37888
	ds_read_b128 v[196:199], v156 offset:38912
	ds_read_b128 v[200:203], v156 offset:39936
	global_load_lds_dwordx4 v[204:205], off
	v_lshl_add_u64 v[204:205], s[34:35], 0, v[132:133]
	s_mov_b32 m0, s42
	s_nop 0
	global_load_lds_dwordx4 v[204:205], off
	s_waitcnt lgkmcnt(8)
	s_barrier
	s_waitcnt lgkmcnt(0)
	s_setprio 1
	s_waitcnt lgkmcnt(0)
	v_mfma_f32_16x16x32_bf16 v[124:127], v[144:147], v[172:175], v[124:127]
	v_mfma_f32_16x16x32_bf16 v[120:123], v[160:163], v[172:175], v[120:123]
	v_mfma_f32_16x16x32_bf16 v[108:111], v[144:147], v[180:183], v[108:111]
	v_mfma_f32_16x16x32_bf16 v[104:107], v[160:163], v[180:183], v[104:107]
	v_mfma_f32_16x16x32_bf16 v[92:95], v[144:147], v[188:191], v[92:95]
	v_mfma_f32_16x16x32_bf16 v[88:91], v[160:163], v[188:191], v[88:91]
	v_mfma_f32_16x16x32_bf16 v[76:79], v[144:147], v[196:199], v[76:79]
	v_mfma_f32_16x16x32_bf16 v[72:75], v[160:163], v[196:199], v[72:75]
	v_mfma_f32_16x16x32_bf16 v[124:127], v[148:151], v[176:179], v[124:127]
	v_mfma_f32_16x16x32_bf16 v[120:123], v[164:167], v[176:179], v[120:123]
	v_mfma_f32_16x16x32_bf16 v[108:111], v[148:151], v[184:187], v[108:111]
	v_mfma_f32_16x16x32_bf16 v[104:107], v[164:167], v[184:187], v[104:107]
	v_mfma_f32_16x16x32_bf16 v[92:95], v[148:151], v[192:195], v[92:95]
	v_mfma_f32_16x16x32_bf16 v[88:91], v[164:167], v[192:195], v[88:91]
	v_mfma_f32_16x16x32_bf16 v[76:79], v[148:151], v[200:203], v[76:79]
	v_mfma_f32_16x16x32_bf16 v[72:75], v[164:167], v[200:203], v[72:75]
	s_setprio 0
	s_barrier
	s_add_i32 s34, 0, 0x1c000
	s_add_i32 s35, s61, s38
	v_add_u32_e32 v159, s34, v153
	v_lshl_add_u64 v[168:169], v[168:169], 0, s[10:11]
	s_mov_b32 m0, s35
	ds_read_b128 v[204:207], v159
	ds_read_b128 v[208:211], v159 offset:1024
	ds_read_b128 v[212:215], v159 offset:2048
	ds_read_b128 v[216:219], v159 offset:3072
	global_load_lds_dwordx4 v[168:169], off
	v_lshl_add_u64 v[168:169], v[220:221], 0, s[10:11]
	s_add_i32 m0, s35, 0x2000
	s_nop 0
	global_load_lds_dwordx4 v[168:169], off
	s_barrier
	s_waitcnt lgkmcnt(0)
	s_setprio 1
	s_waitcnt lgkmcnt(0)
	v_mfma_f32_16x16x32_bf16 v[116:119], v[204:207], v[172:175], v[116:119]
	v_mfma_f32_16x16x32_bf16 v[112:115], v[212:215], v[172:175], v[112:115]
	v_mfma_f32_16x16x32_bf16 v[100:103], v[204:207], v[180:183], v[100:103]
	v_mfma_f32_16x16x32_bf16 v[96:99], v[212:215], v[180:183], v[96:99]
	v_mfma_f32_16x16x32_bf16 v[84:87], v[204:207], v[188:191], v[84:87]
	v_mfma_f32_16x16x32_bf16 v[80:83], v[212:215], v[188:191], v[80:83]
	v_mfma_f32_16x16x32_bf16 v[68:71], v[204:207], v[196:199], v[68:71]
	v_mfma_f32_16x16x32_bf16 v[64:67], v[212:215], v[196:199], v[64:67]
	v_mfma_f32_16x16x32_bf16 v[116:119], v[208:211], v[176:179], v[116:119]
	v_mfma_f32_16x16x32_bf16 v[112:115], v[216:219], v[176:179], v[112:115]
	v_mfma_f32_16x16x32_bf16 v[100:103], v[208:211], v[184:187], v[100:103]
	v_mfma_f32_16x16x32_bf16 v[96:99], v[216:219], v[184:187], v[96:99]
	v_mfma_f32_16x16x32_bf16 v[84:87], v[208:211], v[192:195], v[84:87]
	v_mfma_f32_16x16x32_bf16 v[80:83], v[216:219], v[192:195], v[80:83]
	v_mfma_f32_16x16x32_bf16 v[68:71], v[208:211], v[200:203], v[68:71]
	v_mfma_f32_16x16x32_bf16 v[64:67], v[216:219], v[200:203], v[64:67]
	s_setprio 0
	s_mov_b32 m0, s45
	v_lshl_add_u64 v[168:169], v[222:223], 0, s[10:11]
	s_barrier
	ds_read_b128 v[172:175], v156 offset:49152
	ds_read_b128 v[176:179], v156 offset:50176
	ds_read_b128 v[180:183], v156 offset:51200
	ds_read_b128 v[184:187], v156 offset:52224
	ds_read_b128 v[188:191], v156 offset:53248
	ds_read_b128 v[192:195], v156 offset:54272
	ds_read_b128 v[196:199], v156 offset:55296
	ds_read_b128 v[200:203], v156 offset:56320
	global_load_lds_dwordx4 v[168:169], off
	v_lshl_add_u64 v[168:169], v[224:225], 0, s[10:11]
	s_mov_b32 m0, s46
	s_nop 0
	global_load_lds_dwordx4 v[168:169], off
	s_barrier
	s_waitcnt lgkmcnt(0)
	s_setprio 1
	s_waitcnt lgkmcnt(0)
	v_mfma_f32_16x16x32_bf16 v[60:63], v[144:147], v[172:175], v[60:63]
	v_mfma_f32_16x16x32_bf16 v[56:59], v[160:163], v[172:175], v[56:59]
	v_mfma_f32_16x16x32_bf16 v[44:47], v[144:147], v[180:183], v[44:47]
	v_mfma_f32_16x16x32_bf16 v[40:43], v[160:163], v[180:183], v[40:43]
	v_mfma_f32_16x16x32_bf16 v[28:31], v[144:147], v[188:191], v[28:31]
	v_mfma_f32_16x16x32_bf16 v[24:27], v[160:163], v[188:191], v[24:27]
	v_mfma_f32_16x16x32_bf16 v[12:15], v[144:147], v[196:199], v[12:15]
	v_mfma_f32_16x16x32_bf16 v[8:11], v[160:163], v[196:199], v[8:11]
	v_mfma_f32_16x16x32_bf16 v[60:63], v[148:151], v[176:179], v[60:63]
	v_mfma_f32_16x16x32_bf16 v[56:59], v[164:167], v[176:179], v[56:59]
	v_mfma_f32_16x16x32_bf16 v[44:47], v[148:151], v[184:187], v[44:47]
	v_mfma_f32_16x16x32_bf16 v[40:43], v[164:167], v[184:187], v[40:43]
	v_mfma_f32_16x16x32_bf16 v[28:31], v[148:151], v[192:195], v[28:31]
	v_mfma_f32_16x16x32_bf16 v[24:27], v[164:167], v[192:195], v[24:27]
	v_mfma_f32_16x16x32_bf16 v[12:15], v[148:151], v[200:203], v[12:15]
	v_mfma_f32_16x16x32_bf16 v[8:11], v[164:167], v[200:203], v[8:11]
	s_setprio 0
	s_barrier
	s_add_u32 s30, s30, 0x80080
	s_addc_u32 s31, s31, 0
	s_add_i32 s34, s34, s38
	v_lshl_add_u64 v[144:145], s[30:31], 0, v[130:131]
	s_mov_b32 m0, s34
	s_nop 0
	global_load_lds_dwordx4 v[144:145], off
	v_lshl_add_u64 v[144:145], s[30:31], 0, v[134:135]
	s_add_i32 m0, s34, 0x2000
	s_nop 0
	global_load_lds_dwordx4 v[144:145], off
	s_waitcnt vmcnt(6)
	s_barrier
	s_setprio 1
	v_mfma_f32_16x16x32_bf16 v[52:55], v[204:207], v[172:175], v[52:55]
	v_mfma_f32_16x16x32_bf16 v[48:51], v[212:215], v[172:175], v[48:51]
	v_mfma_f32_16x16x32_bf16 v[36:39], v[204:207], v[180:183], v[36:39]
	v_mfma_f32_16x16x32_bf16 v[32:35], v[212:215], v[180:183], v[32:35]
	v_mfma_f32_16x16x32_bf16 v[20:23], v[204:207], v[188:191], v[20:23]
	v_mfma_f32_16x16x32_bf16 v[16:19], v[212:215], v[188:191], v[16:19]
	v_mfma_f32_16x16x32_bf16 v[4:7], v[204:207], v[196:199], v[4:7]
	v_mfma_f32_16x16x32_bf16 v[0:3], v[212:215], v[196:199], v[0:3]
	v_mfma_f32_16x16x32_bf16 v[52:55], v[208:211], v[176:179], v[52:55]
	v_mfma_f32_16x16x32_bf16 v[48:51], v[216:219], v[176:179], v[48:51]
	v_mfma_f32_16x16x32_bf16 v[36:39], v[208:211], v[184:187], v[36:39]
	v_mfma_f32_16x16x32_bf16 v[32:35], v[216:219], v[184:187], v[32:35]
	v_mfma_f32_16x16x32_bf16 v[20:23], v[208:211], v[192:195], v[20:23]
	v_mfma_f32_16x16x32_bf16 v[16:19], v[216:219], v[192:195], v[16:19]
	v_mfma_f32_16x16x32_bf16 v[4:7], v[208:211], v[200:203], v[4:7]
	v_mfma_f32_16x16x32_bf16 v[0:3], v[216:219], v[200:203], v[0:3]
	s_setprio 0
	s_add_i32 s60, s60, 2
	s_add_u32 s0, s0, 0x100
	s_addc_u32 s1, s1, 0
	s_add_u32 s58, s58, 0x100
	s_addc_u32 s59, s59, 0
	s_cmp_gt_u32 s60, 29
	s_barrier
	s_cbranch_scc0 .LBB0_1271
	v_lshl_add_u32 v148, s28, 8, v152
	v_ashrrev_i32_e32 v149, 31, v148
	v_lshl_add_u64 v[146:147], v[148:149], 2, s[8:9]
	v_lshl_or_b32 v144, s55, 8, v154
	v_ashrrev_i32_e32 v145, 31, v144
	v_lshlrev_b64 v[150:151], 1, v[144:145]
	v_lshlrev_b64 v[162:163], 14, v[148:149]
	v_or_b32_e32 v160, 16, v148
	v_ashrrev_i32_e32 v161, 31, v160
	s_mov_b32 s55, s20
	s_mov_b32 s28, s22
	s_mov_b64 s[30:31], s[26:27]
	s_mov_b64 s[34:35], s[24:25]
	v_fmamk_f32 v144, v236, 0x3a000000, v158
	v_mul_f32_e32 v145, 0x4b800000, v144
	v_cmp_gt_f32_e32 vcc, s50, v144
	s_nop 1
	v_cndmask_b32_e32 v144, v144, v145, vcc
	v_rsq_f32_e32 v149, v144
	v_lshl_add_u64 v[144:145], s[68:69], 0, v[162:163]
	v_lshl_add_u64 v[144:145], v[144:145], 0, v[150:151]
	v_lshl_add_u64 v[162:163], v[160:161], 2, s[8:9]
	v_mul_f32_e32 v159, 0x45800000, v149
	v_cndmask_b32_e32 v164, v149, v159, vcc
	v_pk_mul_f32 v[126:127], v[126:127], v[164:165] op_sel_hi:[1,0]
	v_pk_mul_f32 v[124:125], v[124:125], v[164:165] op_sel_hi:[1,0]
	v_pk_mul_f32 v[122:123], v[122:123], v[164:165] op_sel_hi:[1,0]
	v_pk_mul_f32 v[120:121], v[120:121], v[164:165] op_sel_hi:[1,0]
	v_pk_mul_f32 v[118:119], v[118:119], v[164:165] op_sel_hi:[1,0]
	v_pk_mul_f32 v[116:117], v[116:117], v[164:165] op_sel_hi:[1,0]
	v_pk_mul_f32 v[114:115], v[114:115], v[164:165] op_sel_hi:[1,0]
	v_pk_mul_f32 v[112:113], v[112:113], v[164:165] op_sel_hi:[1,0]
	v_max_f32_e32 v124, 0, v124
	v_max_f32_e32 v120, 0, v120
	v_max_f32_e32 v125, 0, v125
	v_max_f32_e32 v121, 0, v121
	v_max_f32_e32 v126, 0, v126
	v_max_f32_e32 v122, 0, v122
	v_max_f32_e32 v127, 0, v127
	v_max_f32_e32 v123, 0, v123
	v_max_f32_e32 v116, 0, v116
	v_max_f32_e32 v112, 0, v112
	v_max_f32_e32 v117, 0, v117
	v_max_f32_e32 v113, 0, v113
	v_max_f32_e32 v118, 0, v118
	v_max_f32_e32 v114, 0, v114
	v_max_f32_e32 v119, 0, v119
	v_max_f32_e32 v115, 0, v115
	v_mul_f32_e32 v124, v124, v124
	v_mul_f32_e32 v120, v120, v120
	v_mul_f32_e32 v125, v125, v125
	v_mul_f32_e32 v121, v121, v121
	v_mul_f32_e32 v126, v126, v126
	v_mul_f32_e32 v122, v122, v122
	v_mul_f32_e32 v127, v127, v127
	v_mul_f32_e32 v123, v123, v123
	v_mul_f32_e32 v116, v116, v116
	v_mul_f32_e32 v149, v112, v112
	v_mul_f32_e32 v117, v117, v117
	v_mul_f32_e32 v159, v113, v113
	v_mul_f32_e32 v118, v118, v118
	v_mul_f32_e32 v164, v114, v114
	v_mul_f32_e32 v119, v119, v119
	v_mul_f32_e32 v165, v115, v115
	v_cvt_pk_bf16_f32 v112, v124, v125
	v_cvt_pk_bf16_f32 v113, v126, v127
	v_cvt_pk_bf16_f32 v114, v120, v121
	v_cvt_pk_bf16_f32 v115, v122, v123
	v_cvt_pk_bf16_f32 v116, v116, v117
	v_cvt_pk_bf16_f32 v117, v118, v119
	v_cvt_pk_bf16_f32 v118, v149, v159
	v_cvt_pk_bf16_f32 v119, v164, v165
	global_store_dwordx4 v[144:145], v[112:115], off
	global_store_dwordx4 v[144:145], v[116:119], off offset:256
	v_lshlrev_b64 v[114:115], 14, v[160:161]
	v_or_b32_e32 v112, 32, v148
	v_lshl_add_u64 v[114:115], s[68:69], 0, v[114:115]
	v_ashrrev_i32_e32 v113, 31, v112
	v_lshl_add_u64 v[114:115], v[114:115], 0, v[150:151]
	v_fmamk_f32 v116, v237, 0x3a000000, v158
	v_mul_f32_e32 v117, 0x4b800000, v116
	v_cmp_gt_f32_e32 vcc, s50, v116
	s_nop 1
	v_cndmask_b32_e32 v116, v116, v117, vcc
	v_rsq_f32_e32 v118, v116
	v_lshl_add_u64 v[116:117], v[112:113], 2, s[8:9]
	v_mul_f32_e32 v119, 0x45800000, v118
	v_cndmask_b32_e32 v118, v118, v119, vcc
	v_pk_mul_f32 v[110:111], v[110:111], v[118:119] op_sel_hi:[1,0]
	v_pk_mul_f32 v[108:109], v[108:109], v[118:119] op_sel_hi:[1,0]
	v_pk_mul_f32 v[106:107], v[106:107], v[118:119] op_sel_hi:[1,0]
	v_pk_mul_f32 v[104:105], v[104:105], v[118:119] op_sel_hi:[1,0]
	v_pk_mul_f32 v[102:103], v[102:103], v[118:119] op_sel_hi:[1,0]
	v_pk_mul_f32 v[100:101], v[100:101], v[118:119] op_sel_hi:[1,0]
	v_pk_mul_f32 v[98:99], v[98:99], v[118:119] op_sel_hi:[1,0]
	v_pk_mul_f32 v[96:97], v[96:97], v[118:119] op_sel_hi:[1,0]
	v_max_f32_e32 v108, 0, v108
	v_max_f32_e32 v104, 0, v104
	v_max_f32_e32 v109, 0, v109
	v_max_f32_e32 v105, 0, v105
	v_max_f32_e32 v110, 0, v110
	v_max_f32_e32 v106, 0, v106
	v_max_f32_e32 v111, 0, v111
	v_max_f32_e32 v107, 0, v107
	v_max_f32_e32 v100, 0, v100
	v_max_f32_e32 v96, 0, v96
	v_max_f32_e32 v101, 0, v101
	v_max_f32_e32 v97, 0, v97
	v_max_f32_e32 v102, 0, v102
	v_max_f32_e32 v98, 0, v98
	v_max_f32_e32 v103, 0, v103
	v_max_f32_e32 v99, 0, v99
	v_mul_f32_e32 v108, v108, v108
	v_mul_f32_e32 v104, v104, v104
	v_mul_f32_e32 v109, v109, v109
	v_mul_f32_e32 v105, v105, v105
	v_mul_f32_e32 v110, v110, v110
	v_mul_f32_e32 v106, v106, v106
	v_mul_f32_e32 v111, v111, v111
	v_mul_f32_e32 v107, v107, v107
	v_mul_f32_e32 v100, v100, v100
	v_mul_f32_e32 v118, v96, v96
	v_mul_f32_e32 v101, v101, v101
	v_mul_f32_e32 v119, v97, v97
	v_mul_f32_e32 v102, v102, v102
	v_mul_f32_e32 v120, v98, v98
	v_mul_f32_e32 v103, v103, v103
	v_mul_f32_e32 v121, v99, v99
	v_cvt_pk_bf16_f32 v96, v108, v109
	v_cvt_pk_bf16_f32 v97, v110, v111
	v_cvt_pk_bf16_f32 v98, v104, v105
	v_cvt_pk_bf16_f32 v99, v106, v107
	v_cvt_pk_bf16_f32 v100, v100, v101
	v_cvt_pk_bf16_f32 v101, v102, v103
	v_cvt_pk_bf16_f32 v102, v118, v119
	v_cvt_pk_bf16_f32 v103, v120, v121
	global_store_dwordx4 v[114:115], v[96:99], off
	global_store_dwordx4 v[114:115], v[100:103], off offset:256
	v_lshlrev_b64 v[98:99], 14, v[112:113]
	v_or_b32_e32 v96, 48, v148
	v_lshl_add_u64 v[98:99], s[68:69], 0, v[98:99]
	v_ashrrev_i32_e32 v97, 31, v96
	v_lshl_add_u64 v[98:99], v[98:99], 0, v[150:151]
	v_fmamk_f32 v100, v238, 0x3a000000, v158
	v_mul_f32_e32 v101, 0x4b800000, v100
	v_cmp_gt_f32_e32 vcc, s50, v100
	s_nop 1
	v_cndmask_b32_e32 v100, v100, v101, vcc
	v_rsq_f32_e32 v102, v100
	v_lshl_add_u64 v[100:101], v[96:97], 2, s[8:9]
	v_mul_f32_e32 v103, 0x45800000, v102
	v_cndmask_b32_e32 v102, v102, v103, vcc
	v_pk_mul_f32 v[94:95], v[94:95], v[102:103] op_sel_hi:[1,0]
	v_pk_mul_f32 v[92:93], v[92:93], v[102:103] op_sel_hi:[1,0]
	v_pk_mul_f32 v[90:91], v[90:91], v[102:103] op_sel_hi:[1,0]
	v_pk_mul_f32 v[88:89], v[88:89], v[102:103] op_sel_hi:[1,0]
	v_pk_mul_f32 v[86:87], v[86:87], v[102:103] op_sel_hi:[1,0]
	v_pk_mul_f32 v[84:85], v[84:85], v[102:103] op_sel_hi:[1,0]
	v_pk_mul_f32 v[82:83], v[82:83], v[102:103] op_sel_hi:[1,0]
	v_pk_mul_f32 v[80:81], v[80:81], v[102:103] op_sel_hi:[1,0]
	v_max_f32_e32 v92, 0, v92
	v_max_f32_e32 v88, 0, v88
	v_max_f32_e32 v93, 0, v93
	v_max_f32_e32 v89, 0, v89
	v_max_f32_e32 v94, 0, v94
	v_max_f32_e32 v90, 0, v90
	v_max_f32_e32 v95, 0, v95
	v_max_f32_e32 v91, 0, v91
	v_max_f32_e32 v84, 0, v84
	v_max_f32_e32 v80, 0, v80
	v_max_f32_e32 v85, 0, v85
	v_max_f32_e32 v81, 0, v81
	v_max_f32_e32 v86, 0, v86
	v_max_f32_e32 v82, 0, v82
	v_max_f32_e32 v87, 0, v87
	v_max_f32_e32 v83, 0, v83
	v_mul_f32_e32 v92, v92, v92
	v_mul_f32_e32 v88, v88, v88
	v_mul_f32_e32 v93, v93, v93
	v_mul_f32_e32 v89, v89, v89
	v_mul_f32_e32 v94, v94, v94
	v_mul_f32_e32 v90, v90, v90
	v_mul_f32_e32 v95, v95, v95
	v_mul_f32_e32 v91, v91, v91
	v_mul_f32_e32 v84, v84, v84
	v_mul_f32_e32 v102, v80, v80
	v_mul_f32_e32 v85, v85, v85
	v_mul_f32_e32 v103, v81, v81
	v_mul_f32_e32 v86, v86, v86
	v_mul_f32_e32 v104, v82, v82
	v_mul_f32_e32 v87, v87, v87
	v_mul_f32_e32 v105, v83, v83
	v_cvt_pk_bf16_f32 v80, v92, v93
	v_cvt_pk_bf16_f32 v81, v94, v95
	v_cvt_pk_bf16_f32 v82, v88, v89
	v_cvt_pk_bf16_f32 v83, v90, v91
	v_cvt_pk_bf16_f32 v84, v84, v85
	v_cvt_pk_bf16_f32 v85, v86, v87
	v_cvt_pk_bf16_f32 v86, v102, v103
	v_cvt_pk_bf16_f32 v87, v104, v105
	global_store_dwordx4 v[98:99], v[80:83], off
	global_store_dwordx4 v[98:99], v[84:87], off offset:256
	v_fmamk_f32 v80, v239, 0x3a000000, v158
	v_mul_f32_e32 v81, 0x4b800000, v80
	v_cmp_gt_f32_e32 vcc, s50, v80
	s_nop 1
	v_cndmask_b32_e32 v80, v80, v81, vcc
	v_rsq_f32_e32 v82, v80
	v_lshlrev_b64 v[80:81], 14, v[96:97]
	v_lshl_add_u64 v[80:81], s[68:69], 0, v[80:81]
	v_lshl_add_u64 v[80:81], v[80:81], 0, v[150:151]
	v_mul_f32_e32 v83, 0x45800000, v82
	v_cndmask_b32_e32 v82, v82, v83, vcc
	v_pk_mul_f32 v[78:79], v[78:79], v[82:83] op_sel_hi:[1,0]
	v_pk_mul_f32 v[76:77], v[76:77], v[82:83] op_sel_hi:[1,0]
	v_pk_mul_f32 v[74:75], v[74:75], v[82:83] op_sel_hi:[1,0]
	v_pk_mul_f32 v[72:73], v[72:73], v[82:83] op_sel_hi:[1,0]
	v_pk_mul_f32 v[70:71], v[70:71], v[82:83] op_sel_hi:[1,0]
	v_pk_mul_f32 v[68:69], v[68:69], v[82:83] op_sel_hi:[1,0]
	v_pk_mul_f32 v[66:67], v[66:67], v[82:83] op_sel_hi:[1,0]
	v_pk_mul_f32 v[64:65], v[64:65], v[82:83] op_sel_hi:[1,0]
	v_max_f32_e32 v76, 0, v76
	v_max_f32_e32 v72, 0, v72
	v_max_f32_e32 v77, 0, v77
	v_max_f32_e32 v73, 0, v73
	v_max_f32_e32 v78, 0, v78
	v_max_f32_e32 v74, 0, v74
	v_max_f32_e32 v79, 0, v79
	v_max_f32_e32 v75, 0, v75
	v_max_f32_e32 v68, 0, v68
	v_max_f32_e32 v64, 0, v64
	v_max_f32_e32 v69, 0, v69
	v_max_f32_e32 v65, 0, v65
	v_max_f32_e32 v70, 0, v70
	v_max_f32_e32 v66, 0, v66
	v_max_f32_e32 v71, 0, v71
	v_max_f32_e32 v67, 0, v67
	v_mul_f32_e32 v76, v76, v76
	v_mul_f32_e32 v72, v72, v72
	v_mul_f32_e32 v77, v77, v77
	v_mul_f32_e32 v73, v73, v73
	v_mul_f32_e32 v78, v78, v78
	v_mul_f32_e32 v74, v74, v74
	v_mul_f32_e32 v79, v79, v79
	v_mul_f32_e32 v75, v75, v75
	v_mul_f32_e32 v68, v68, v68
	v_mul_f32_e32 v82, v64, v64
	v_mul_f32_e32 v69, v69, v69
	v_mul_f32_e32 v83, v65, v65
	v_mul_f32_e32 v70, v70, v70
	v_mul_f32_e32 v84, v66, v66
	v_mul_f32_e32 v71, v71, v71
	v_mul_f32_e32 v85, v67, v67
	v_cvt_pk_bf16_f32 v64, v76, v77
	v_cvt_pk_bf16_f32 v65, v78, v79
	v_cvt_pk_bf16_f32 v66, v72, v73
	v_cvt_pk_bf16_f32 v67, v74, v75
	v_cvt_pk_bf16_f32 v68, v68, v69
	v_cvt_pk_bf16_f32 v69, v70, v71
	v_cvt_pk_bf16_f32 v70, v82, v83
	v_cvt_pk_bf16_f32 v71, v84, v85
	global_store_dwordx4 v[80:81], v[64:67], off
	global_store_dwordx4 v[80:81], v[68:71], off offset:256
	v_lshl_add_u64 v[64:65], v[144:145], 0, s[12:13]
	v_fmamk_f32 v66, v240, 0x3a000000, v158
	v_mul_f32_e32 v67, 0x4b800000, v66
	v_cmp_gt_f32_e32 vcc, s50, v66
	s_nop 1
	v_cndmask_b32_e32 v66, v66, v67, vcc
	v_rsq_f32_e32 v68, v66
	v_add_co_u32_e64 v66, s[0:1], s51, v144
	v_mul_f32_e32 v69, 0x45800000, v68
	v_cndmask_b32_e32 v68, v68, v69, vcc
	v_pk_mul_f32 v[62:63], v[62:63], v[68:69] op_sel_hi:[1,0]
	v_pk_mul_f32 v[60:61], v[60:61], v[68:69] op_sel_hi:[1,0]
	v_pk_mul_f32 v[58:59], v[58:59], v[68:69] op_sel_hi:[1,0]
	v_pk_mul_f32 v[56:57], v[56:57], v[68:69] op_sel_hi:[1,0]
	v_pk_mul_f32 v[54:55], v[54:55], v[68:69] op_sel_hi:[1,0]
	v_pk_mul_f32 v[52:53], v[52:53], v[68:69] op_sel_hi:[1,0]
	v_pk_mul_f32 v[50:51], v[50:51], v[68:69] op_sel_hi:[1,0]
	v_pk_mul_f32 v[48:49], v[48:49], v[68:69] op_sel_hi:[1,0]
	v_max_f32_e32 v60, 0, v60
	v_max_f32_e32 v56, 0, v56
	v_max_f32_e32 v61, 0, v61
	v_max_f32_e32 v57, 0, v57
	v_max_f32_e32 v62, 0, v62
	v_max_f32_e32 v58, 0, v58
	v_max_f32_e32 v63, 0, v63
	v_max_f32_e32 v59, 0, v59
	v_max_f32_e32 v52, 0, v52
	v_max_f32_e32 v48, 0, v48
	v_max_f32_e32 v53, 0, v53
	v_max_f32_e32 v49, 0, v49
	v_max_f32_e32 v54, 0, v54
	v_max_f32_e32 v50, 0, v50
	v_max_f32_e32 v55, 0, v55
	v_max_f32_e32 v51, 0, v51
	v_mul_f32_e32 v60, v60, v60
	v_mul_f32_e32 v56, v56, v56
	v_mul_f32_e32 v61, v61, v61
	v_mul_f32_e32 v57, v57, v57
	v_mul_f32_e32 v62, v62, v62
	v_mul_f32_e32 v58, v58, v58
	v_mul_f32_e32 v63, v63, v63
	v_mul_f32_e32 v59, v59, v59
	v_addc_co_u32_e64 v67, s[0:1], 0, v145, s[0:1]
	v_mul_f32_e32 v52, v52, v52
	v_mul_f32_e32 v68, v48, v48
	v_mul_f32_e32 v53, v53, v53
	v_mul_f32_e32 v69, v49, v49
	v_mul_f32_e32 v54, v54, v54
	v_mul_f32_e32 v70, v50, v50
	v_mul_f32_e32 v55, v55, v55
	v_mul_f32_e32 v71, v51, v51
	v_cvt_pk_bf16_f32 v48, v60, v61
	v_cvt_pk_bf16_f32 v49, v62, v63
	v_cvt_pk_bf16_f32 v50, v56, v57
	v_cvt_pk_bf16_f32 v51, v58, v59
	v_cvt_pk_bf16_f32 v52, v52, v53
	v_cvt_pk_bf16_f32 v53, v54, v55
	v_cvt_pk_bf16_f32 v54, v68, v69
	v_cvt_pk_bf16_f32 v55, v70, v71
	global_store_dwordx4 v[66:67], v[48:51], off
	global_store_dwordx4 v[64:65], v[52:55], off offset:256
	v_lshl_add_u64 v[48:49], v[144:145], 0, s[14:15]
	v_fmamk_f32 v50, v241, 0x3a000000, v158
	v_mul_f32_e32 v51, 0x4b800000, v50
	v_cmp_gt_f32_e32 vcc, s50, v50
	s_nop 1
	v_cndmask_b32_e32 v50, v50, v51, vcc
	v_rsq_f32_e32 v52, v50
	v_add_co_u32_e64 v50, s[0:1], s52, v144
	v_mul_f32_e32 v53, 0x45800000, v52
	v_cndmask_b32_e32 v52, v52, v53, vcc
	v_pk_mul_f32 v[46:47], v[46:47], v[52:53] op_sel_hi:[1,0]
	v_pk_mul_f32 v[44:45], v[44:45], v[52:53] op_sel_hi:[1,0]
	v_pk_mul_f32 v[42:43], v[42:43], v[52:53] op_sel_hi:[1,0]
	v_pk_mul_f32 v[40:41], v[40:41], v[52:53] op_sel_hi:[1,0]
	v_pk_mul_f32 v[38:39], v[38:39], v[52:53] op_sel_hi:[1,0]
	v_pk_mul_f32 v[36:37], v[36:37], v[52:53] op_sel_hi:[1,0]
	v_pk_mul_f32 v[34:35], v[34:35], v[52:53] op_sel_hi:[1,0]
	v_pk_mul_f32 v[32:33], v[32:33], v[52:53] op_sel_hi:[1,0]
	v_max_f32_e32 v44, 0, v44
	v_max_f32_e32 v40, 0, v40
	v_max_f32_e32 v45, 0, v45
	v_max_f32_e32 v41, 0, v41
	v_max_f32_e32 v46, 0, v46
	v_max_f32_e32 v42, 0, v42
	v_max_f32_e32 v47, 0, v47
	v_max_f32_e32 v43, 0, v43
	v_max_f32_e32 v36, 0, v36
	v_max_f32_e32 v32, 0, v32
	v_max_f32_e32 v37, 0, v37
	v_max_f32_e32 v33, 0, v33
	v_max_f32_e32 v38, 0, v38
	v_max_f32_e32 v34, 0, v34
	v_max_f32_e32 v39, 0, v39
	v_max_f32_e32 v35, 0, v35
	v_mul_f32_e32 v44, v44, v44
	v_mul_f32_e32 v40, v40, v40
	v_mul_f32_e32 v45, v45, v45
	v_mul_f32_e32 v41, v41, v41
	v_mul_f32_e32 v46, v46, v46
	v_mul_f32_e32 v42, v42, v42
	v_mul_f32_e32 v47, v47, v47
	v_mul_f32_e32 v43, v43, v43
	v_addc_co_u32_e64 v51, s[0:1], 0, v145, s[0:1]
	v_mul_f32_e32 v36, v36, v36
	v_mul_f32_e32 v52, v32, v32
	v_mul_f32_e32 v37, v37, v37
	v_mul_f32_e32 v53, v33, v33
	v_mul_f32_e32 v38, v38, v38
	v_mul_f32_e32 v54, v34, v34
	v_mul_f32_e32 v39, v39, v39
	v_mul_f32_e32 v55, v35, v35
	v_cvt_pk_bf16_f32 v32, v44, v45
	v_cvt_pk_bf16_f32 v33, v46, v47
	v_cvt_pk_bf16_f32 v34, v40, v41
	v_cvt_pk_bf16_f32 v35, v42, v43
	v_cvt_pk_bf16_f32 v36, v36, v37
	v_cvt_pk_bf16_f32 v37, v38, v39
	v_cvt_pk_bf16_f32 v38, v52, v53
	v_cvt_pk_bf16_f32 v39, v54, v55
	global_store_dwordx4 v[50:51], v[32:35], off
	global_store_dwordx4 v[48:49], v[36:39], off offset:256
	v_lshl_add_u64 v[32:33], v[144:145], 0, s[16:17]
	v_fmamk_f32 v34, v242, 0x3a000000, v158
	v_mul_f32_e32 v35, 0x4b800000, v34
	v_cmp_gt_f32_e32 vcc, s50, v34
	s_nop 1
	v_cndmask_b32_e32 v34, v34, v35, vcc
	v_rsq_f32_e32 v36, v34
	v_add_co_u32_e64 v34, s[0:1], s53, v144
	v_mul_f32_e32 v37, 0x45800000, v36
	v_cndmask_b32_e32 v36, v36, v37, vcc
	v_pk_mul_f32 v[30:31], v[30:31], v[36:37] op_sel_hi:[1,0]
	v_pk_mul_f32 v[28:29], v[28:29], v[36:37] op_sel_hi:[1,0]
	v_pk_mul_f32 v[26:27], v[26:27], v[36:37] op_sel_hi:[1,0]
	v_pk_mul_f32 v[24:25], v[24:25], v[36:37] op_sel_hi:[1,0]
	v_pk_mul_f32 v[22:23], v[22:23], v[36:37] op_sel_hi:[1,0]
	v_pk_mul_f32 v[20:21], v[20:21], v[36:37] op_sel_hi:[1,0]
	v_pk_mul_f32 v[18:19], v[18:19], v[36:37] op_sel_hi:[1,0]
	v_pk_mul_f32 v[16:17], v[16:17], v[36:37] op_sel_hi:[1,0]
	v_max_f32_e32 v28, 0, v28
	v_max_f32_e32 v24, 0, v24
	v_max_f32_e32 v29, 0, v29
	v_max_f32_e32 v25, 0, v25
	v_max_f32_e32 v30, 0, v30
	v_max_f32_e32 v26, 0, v26
	v_max_f32_e32 v31, 0, v31
	v_max_f32_e32 v27, 0, v27
	v_max_f32_e32 v20, 0, v20
	v_max_f32_e32 v16, 0, v16
	v_max_f32_e32 v21, 0, v21
	v_max_f32_e32 v17, 0, v17
	v_max_f32_e32 v22, 0, v22
	v_max_f32_e32 v18, 0, v18
	v_max_f32_e32 v23, 0, v23
	v_max_f32_e32 v19, 0, v19
	v_mul_f32_e32 v28, v28, v28
	v_mul_f32_e32 v24, v24, v24
	v_mul_f32_e32 v29, v29, v29
	v_mul_f32_e32 v25, v25, v25
	v_mul_f32_e32 v30, v30, v30
	v_mul_f32_e32 v26, v26, v26
	v_mul_f32_e32 v31, v31, v31
	v_mul_f32_e32 v27, v27, v27
	v_addc_co_u32_e64 v35, s[0:1], 0, v145, s[0:1]
	v_mul_f32_e32 v20, v20, v20
	v_mul_f32_e32 v36, v16, v16
	v_mul_f32_e32 v21, v21, v21
	v_mul_f32_e32 v37, v17, v17
	v_mul_f32_e32 v22, v22, v22
	v_mul_f32_e32 v38, v18, v18
	v_mul_f32_e32 v23, v23, v23
	v_mul_f32_e32 v39, v19, v19
	v_cvt_pk_bf16_f32 v16, v28, v29
	v_cvt_pk_bf16_f32 v17, v30, v31
	v_cvt_pk_bf16_f32 v18, v24, v25
	v_cvt_pk_bf16_f32 v19, v26, v27
	v_cvt_pk_bf16_f32 v20, v20, v21
	v_cvt_pk_bf16_f32 v21, v22, v23
	v_cvt_pk_bf16_f32 v22, v36, v37
	v_cvt_pk_bf16_f32 v23, v38, v39
	global_store_dwordx4 v[34:35], v[16:19], off
	global_store_dwordx4 v[32:33], v[20:23], off offset:256
	s_and_b64 vcc, exec, s[2:3]
	v_lshl_add_u64 v[16:17], v[144:145], 0, s[18:19]
	v_fmamk_f32 v18, v243, 0x3a000000, v158
	v_mul_f32_e32 v19, 0x4b800000, v18
	v_cmp_gt_f32_e64 s[0:1], s50, v18
	s_nop 1
	v_cndmask_b32_e64 v18, v18, v19, s[0:1]
	v_rsq_f32_e32 v20, v18
	v_add_co_u32_e64 v18, s[2:3], s54, v144
	v_mul_f32_e32 v21, 0x45800000, v20
	v_cndmask_b32_e64 v20, v20, v21, s[0:1]
	v_pk_mul_f32 v[14:15], v[14:15], v[20:21] op_sel_hi:[1,0]
	v_pk_mul_f32 v[12:13], v[12:13], v[20:21] op_sel_hi:[1,0]
	v_pk_mul_f32 v[10:11], v[10:11], v[20:21] op_sel_hi:[1,0]
	v_pk_mul_f32 v[8:9], v[8:9], v[20:21] op_sel_hi:[1,0]
	v_pk_mul_f32 v[6:7], v[6:7], v[20:21] op_sel_hi:[1,0]
	v_pk_mul_f32 v[4:5], v[4:5], v[20:21] op_sel_hi:[1,0]
	v_pk_mul_f32 v[2:3], v[2:3], v[20:21] op_sel_hi:[1,0]
	v_pk_mul_f32 v[0:1], v[0:1], v[20:21] op_sel_hi:[1,0]
	v_max_f32_e32 v12, 0, v12
	v_max_f32_e32 v8, 0, v8
	v_max_f32_e32 v13, 0, v13
	v_max_f32_e32 v9, 0, v9
	v_max_f32_e32 v14, 0, v14
	v_max_f32_e32 v10, 0, v10
	v_max_f32_e32 v15, 0, v15
	v_max_f32_e32 v11, 0, v11
	v_max_f32_e32 v4, 0, v4
	v_max_f32_e32 v0, 0, v0
	v_max_f32_e32 v5, 0, v5
	v_max_f32_e32 v1, 0, v1
	v_max_f32_e32 v6, 0, v6
	v_max_f32_e32 v2, 0, v2
	v_max_f32_e32 v7, 0, v7
	v_max_f32_e32 v3, 0, v3
	v_mul_f32_e32 v12, v12, v12
	v_mul_f32_e32 v8, v8, v8
	v_mul_f32_e32 v13, v13, v13
	v_mul_f32_e32 v9, v9, v9
	v_mul_f32_e32 v14, v14, v14
	v_mul_f32_e32 v10, v10, v10
	v_mul_f32_e32 v15, v15, v15
	v_mul_f32_e32 v11, v11, v11
	v_addc_co_u32_e64 v19, s[2:3], 0, v145, s[2:3]
	v_mul_f32_e32 v4, v4, v4
	v_mul_f32_e32 v20, v0, v0
	v_mul_f32_e32 v5, v5, v5
	v_mul_f32_e32 v21, v1, v1
	v_mul_f32_e32 v6, v6, v6
	v_mul_f32_e32 v22, v2, v2
	v_mul_f32_e32 v7, v7, v7
	v_mul_f32_e32 v23, v3, v3
	v_cvt_pk_bf16_f32 v0, v12, v13
	v_cvt_pk_bf16_f32 v1, v14, v15
	v_cvt_pk_bf16_f32 v2, v8, v9
	v_cvt_pk_bf16_f32 v3, v10, v11
	v_cvt_pk_bf16_f32 v4, v4, v5
	v_cvt_pk_bf16_f32 v5, v6, v7
	v_cvt_pk_bf16_f32 v6, v20, v21
	v_cvt_pk_bf16_f32 v7, v22, v23
	global_store_dwordx4 v[18:19], v[0:3], off
	global_store_dwordx4 v[16:17], v[4:7], off offset:256
	s_cbranch_vccz .LBB0_1264
	s_waitcnt vmcnt(0)
	s_cmpk_gt_u32 s33, 0xff
	s_cbranch_scc1 .LBB0_1275
	s_barrier
